# MLA attention loop unrolled 2x with precomputed per-parity LDS addresses (removes six VALU and seven SALU address ops per iteration)
# speedup vs baseline: 1.0582x; 1.0020x over previous
; DI float bflo(u32 v) { return __uint_as_float(v << 16); }
; DI float bfhi(u32 v) { return __uint_as_float(v & 0xffff0000u); }
; DI float shx(float v, int k) { return __int_as_float(__builtin_amdgcn_ds_bpermute((lane_id_l() ^ k) << 2, __float_as_int(v))); }
; DI void mla_attn_item(const WsPtrs& W, const float* pgq, const float* pgk, int item, unsigned char* smem) {
;     ...
;   for (int i = lane; i < 192; i += 64) { gq = fmaxf(gq, fabsf(pgq[i])); gk = fmaxf(gk, fabsf(pgk[i])); }
; #pragma unroll
;   for (int of = 32; of > 0; of >>= 1) { gq = fmaxf(gq, shx(gq, of)); gk = fmaxf(gk, shx(gk, of)); }
;   const float M = 19.99f * gq * gk * 1.02f + 1.f;
;   bf16x8 qn[12];
;   {
;     const u16* Qr = W.QC + (tokb + q0 + r) * 1536 + hh * 192 + 8 * h;
;     u32x4 raw[12];
; #pragma unroll
;     for (int ks = 0; ks < 12; ++ks) raw[ks] = *(const u32x4*)(Qr + 16 * ks);
;     float ss = 0.f;
; #pragma unroll
;     for (int ks = 0; ks < 12; ++ks) {
;       float a;
;       a = bflo(raw[ks].x); ss += a * a; a = bfhi(raw[ks].x); ss += a * a; a = bflo(raw[ks].y); ss += a * a; a = bfhi(raw[ks].y); ss += a * a;
;       a = bflo(raw[ks].z); ss += a * a; a = bfhi(raw[ks].z); ss += a * a; a = bflo(raw[ks].w); ss += a * a; a = bfhi(raw[ks].w); ss += a * a;
;     }
;     ss += shx(ss, 32);
;     const float sc = rsqrtf(ss * (1.f / 192.f) + EPSV) * (0.07216878364870322f * LOG2E);
;     const float pos = (float)(q0 + r);
;     auto scaled = [&](int ks, float (&v)[8]) __attribute__((always_inline)) {
;       const f32x4 g0 = *(const f32x4*)(pgq + 16 * ks + 8 * h), g1 = *(const f32x4*)(pgq + 16 * ks + 8 * h + 4);
.LBB0_587:
	global_load_dword v11, v[2:3], off
	v_max_f32_e32 v0, v0, v0
	v_add_u32_e32 v10, 64, v10
	s_movk_i32 s2, 0x7f
	v_max_f32_e32 v8, v8, v8
	v_cmp_lt_u32_e32 vcc, s2, v10
	v_lshl_add_u64 v[2:3], v[2:3], 0, s[76:77]
	s_or_b64 s[6:7], vcc, s[6:7]
	s_waitcnt vmcnt(0)
	v_max_f32_e64 v11, |v11|, |v11|
	v_max_f32_e32 v0, v0, v11
	global_load_dword v11, v[4:5], off
	v_lshl_add_u64 v[4:5], v[4:5], 0, s[76:77]
	s_waitcnt vmcnt(0)
	v_max_f32_e64 v11, |v11|, |v11|
	v_max_f32_e32 v8, v8, v11
	s_andn2_b64 exec, exec, s[6:7]
	s_cbranch_execnz .LBB0_587
	s_or_b64 exec, exec, s[6:7]
	v_readlane_b32 s2, v254, 28
	s_ashr_i32 s5, s4, 31
	s_sub_i32 s16, s18, s2
	s_lshl_b64 s[6:7], s[4:5], 23
	s_lshl_b64 s[8:9], s[4:5], 25
	s_mul_i32 s5, s4, 0x6604000
	s_mul_hi_i32 s2, s4, 0x6604000
	s_add_u32 s5, s8, s5
	s_addc_u32 s2, s9, s2
	s_add_u32 s5, s5, 0x7046100
	s_addc_u32 s14, s2, 0
	s_add_u32 s6, s5, s6
	s_addc_u32 s7, s14, s7
	s_add_u32 s8, s62, s6
	v_mov_b32_e32 v3, v229
	s_mul_i32 s10, s4, 0xc00000
	s_addc_u32 s9, s63, s7
	v_mov_b32_e32 v4, v229
	s_mul_hi_i32 s2, s4, 0xc00000
	s_add_u32 s11, s8, s10
	v_lshlrev_b32_e32 v3, 2, v3
	s_addc_u32 s12, s9, s2
	s_lshr_b32 s6, s16, 1
	v_xor_b32_e32 v3, 0x80, v3
	v_lshlrev_b32_e32 v4, 2, v4
	s_and_b32 s13, s6, 0xffffff8
	ds_bpermute_b32 v3, v3, v0
	v_xor_b32_e32 v4, 0x80, v4
	s_or_b32 s15, s13, s81
	s_bfe_i32 s6, s16, 0x190004
	ds_bpermute_b32 v4, v4, v8
	s_add_u32 s5, s62, s5
	v_ashrrev_i32_e32 v2, 1, v9
	s_addc_u32 s14, s63, s14
	s_lshl_b32 s16, s16, 8
	v_and_b32_e32 v2, 0xffffffe0, v2
	s_and_b32 s16, s16, 0xf00
	v_add_u32_e32 v10, s16, v2
	s_waitcnt lgkmcnt(1)
	v_max_f32_e32 v2, v3, v3
	v_max_f32_e32 v0, v0, v0
	v_max_f32_e32 v9, v0, v2
	s_waitcnt lgkmcnt(0)
	v_max_f32_e32 v0, v4, v4
	v_max_f32_e32 v2, v8, v8
	v_max_f32_e32 v8, v2, v0
	v_mov_b32_e32 v0, v229
	s_ashr_i32 s7, s6, 31
	v_lshlrev_b32_e32 v0, 2, v0
	v_xor_b32_e32 v0, 64, v0
	s_lshl_b64 s[16:17], s[6:7], 12
	v_ashrrev_i32_e32 v11, 31, v10
	ds_bpermute_b32 v12, v0, v9
	v_mov_b32_e32 v0, v229
	v_and_b32_e32 v22, 31, v7
	v_lshl_add_u64 v[182:183], s[16:17], 0, v[10:11]
	v_or_b32_e32 v182, v182, v22
	v_mov_b64_e32 v[2:3], s[8:9]
	s_movk_i32 s7, 0xc00
	v_readlane_b32 s20, v255, 23
	v_lshlrev_b32_e32 v0, 2, v0
	v_mad_u64_u32 v[2:3], s[8:9], v182, s7, v[2:3]
	v_readlane_b32 s21, v255, 24
	v_lshrrev_b32_e32 v223, 5, v6
	v_xor_b32_e32 v0, 64, v0
	v_mad_i32_i24 v3, v183, s7, v3
	s_mov_b32 s21, s3
	ds_bpermute_b32 v13, v0, v8
	v_lshl_add_u64 v[2:3], v[2:3], 0, s[20:21]
	v_lshlrev_b32_e32 v0, 4, v223
	v_readlane_b32 s8, v253, 54
	v_mov_b32_e32 v14, v229
	v_mov_b32_e32 v15, v229
	v_mov_b32_e32 v16, v229
	v_mov_b32_e32 v17, v229
	v_mov_b32_e32 v18, v229
	v_mov_b32_e32 v19, v229
	v_mov_b32_e32 v20, v229
	v_mov_b32_e32 v21, v229
	v_lshl_add_u64 v[2:3], v[2:3], 0, v[0:1]
	v_mov_b32_e32 v11, v229
	v_and_b32_e32 v154, 32, v6
	v_readlane_b32 s9, v253, 55
	global_load_dwordx4 v[98:101], v[2:3], off
	global_load_dwordx4 v[106:109], v[2:3], off offset:32
	global_load_dwordx4 v[110:113], v[2:3], off offset:64
	global_load_dwordx4 v[114:117], v[2:3], off offset:96
	global_load_dwordx4 v[118:121], v[2:3], off offset:128
	global_load_dwordx4 v[122:125], v[2:3], off offset:160
	global_load_dwordx4 v[126:129], v[2:3], off offset:192
	global_load_dwordx4 v[130:133], v[2:3], off offset:224
	global_load_dwordx4 v[138:141], v[2:3], off offset:256
	global_load_dwordx4 v[146:149], v[2:3], off offset:288
	global_load_dwordx4 v[134:137], v[2:3], off offset:320
	global_load_dwordx4 v[142:145], v[2:3], off offset:352
	global_load_dwordx4 v[2:5], v154, s[8:9] offset:32
	s_waitcnt lgkmcnt(0)
	v_max_f32_e32 v6, v13, v13
	v_max_f32_e32 v0, v12, v12
	v_max_f32_e32 v12, v8, v6
	v_lshlrev_b32_e32 v6, 2, v14
	v_max_f32_e32 v0, v9, v0
	v_xor_b32_e32 v6, 32, v6
	ds_bpermute_b32 v13, v6, v0
	v_lshlrev_b32_e32 v6, 2, v15
	v_xor_b32_e32 v6, 32, v6
	ds_bpermute_b32 v14, v6, v12
	global_load_dwordx4 v[6:9], v154, s[8:9] offset:48
	global_load_dwordx4 v[168:171], v154, s[8:9] offset:96
	global_load_dwordx4 v[102:105], v154, s[8:9] offset:112
	s_waitcnt lgkmcnt(1)
	v_max_f32_e32 v13, v13, v13
	v_max_f32_e32 v0, v0, v13
	s_waitcnt lgkmcnt(0)
	v_max_f32_e32 v13, v14, v14
	v_or_b32_e32 v10, v10, v22
	v_max_f32_e32 v12, v12, v13
	v_lshlrev_b32_e32 v13, 2, v16
	v_cvt_f32_i32_e32 v224, v10
	v_xor_b32_e32 v13, 16, v13
	v_lshlrev_b32_e32 v14, 2, v17
	ds_bpermute_b32 v13, v13, v0
	v_xor_b32_e32 v14, 16, v14
	ds_bpermute_b32 v14, v14, v12
	v_lshlrev_b32_e32 v11, 2, v11
	v_xor_b32_e32 v155, 0x80, v11
	s_waitcnt lgkmcnt(1)
	v_max_f32_e32 v13, v13, v13
	v_max_f32_e32 v0, v0, v13
	s_waitcnt lgkmcnt(0)
	v_max_f32_e32 v13, v14, v14
	v_max_f32_e32 v12, v12, v13
	v_lshlrev_b32_e32 v13, 2, v18
	v_xor_b32_e32 v13, 8, v13
	v_lshlrev_b32_e32 v14, 2, v19
	ds_bpermute_b32 v13, v13, v0
	v_xor_b32_e32 v14, 8, v14
	ds_bpermute_b32 v14, v14, v12
	global_load_dwordx4 v[90:93], v154, s[52:53] offset:16
	global_load_dwordx4 v[94:97], v154, s[52:53]
	global_load_dwordx4 v[82:85], v154, s[52:53] offset:80
	global_load_dwordx4 v[86:89], v154, s[52:53] offset:64
	global_load_dwordx4 v[74:77], v154, s[52:53] offset:144
	global_load_dwordx4 v[78:81], v154, s[52:53] offset:128
	global_load_dwordx4 v[66:69], v154, s[52:53] offset:208
	global_load_dwordx4 v[70:73], v154, s[52:53] offset:192
	global_load_dwordx4 v[58:61], v154, s[52:53] offset:272
	global_load_dwordx4 v[62:65], v154, s[52:53] offset:256
	global_load_dwordx4 v[50:53], v154, s[52:53] offset:336
	global_load_dwordx4 v[54:57], v154, s[52:53] offset:320
	global_load_dwordx4 v[42:45], v154, s[52:53] offset:400
	global_load_dwordx4 v[46:49], v154, s[52:53] offset:384
	global_load_dwordx4 v[34:37], v154, s[52:53] offset:464
	global_load_dwordx4 v[38:41], v154, s[52:53] offset:448
	s_mov_b32 s7, 0x800000
	s_waitcnt lgkmcnt(1)
; DI float bflo(u32 v) { return __uint_as_float(v << 16); }
; DI float bfhi(u32 v) { return __uint_as_float(v & 0xffff0000u); }
; DI void mla_attn_item(const WsPtrs& W, const float* pgq, const float* pgk, int item, unsigned char* smem) {
;     ...
;   for (int of = 32; of > 0; of >>= 1) { gq = fmaxf(gq, shx(gq, of)); gk = fmaxf(gk, shx(gk, of)); }
;   const float M = 19.99f * gq * gk * 1.02f + 1.f;
;   bf16x8 qn[12];
;   {
;     const u16* Qr = W.QC + (tokb + q0 + r) * 1536 + hh * 192 + 8 * h;
;     u32x4 raw[12];
; #pragma unroll
;     for (int ks = 0; ks < 12; ++ks) raw[ks] = *(const u32x4*)(Qr + 16 * ks);
;     float ss = 0.f;
; #pragma unroll
;     for (int ks = 0; ks < 12; ++ks) {
;       float a;
;       a = bflo(raw[ks].x); ss += a * a; a = bfhi(raw[ks].x); ss += a * a; a = bflo(raw[ks].y); ss += a * a; a = bfhi(raw[ks].y); ss += a * a;
;       a = bflo(raw[ks].z); ss += a * a; a = bfhi(raw[ks].z); ss += a * a; a = bflo(raw[ks].w); ss += a * a; a = bfhi(raw[ks].w); ss += a * a;
;     }
;     ss += shx(ss, 32);
;     const float sc = rsqrtf(ss * (1.f / 192.f) + EPSV) * (0.07216878364870322f * LOG2E);
;     const float pos = (float)(q0 + r);
;     auto scaled = [&](int ks, float (&v)[8]) __attribute__((always_inline)) {
;       const f32x4 g0 = *(const f32x4*)(pgq + 16 * ks + 8 * h), g1 = *(const f32x4*)(pgq + 16 * ks + 8 * h + 4);
;       v[0] = bflo(raw[ks].x) * sc * g0.x; v[1] = bfhi(raw[ks].x) * sc * g0.y; v[2] = bflo(raw[ks].y) * sc * g0.z; v[3] = bfhi(raw[ks].y) * sc * g0.w;
;       v[4] = bflo(raw[ks].z) * sc * g1.x; v[5] = bfhi(raw[ks].z) * sc * g1.y; v[6] = bflo(raw[ks].w) * sc * g1.z; v[7] = bfhi(raw[ks].w) * sc * g1.w;
;     };
;     auto packed = [&](const float (&v)[8]) __attribute__((always_inline)) {
;       u32x4 p; p.x = pack2(v[0], v[1]); p.y = pack2(v[2], v[3]); p.z = pack2(v[4], v[5]); p.w = pack2(v[6], v[7]);
;       return __builtin_bit_cast(bf16x8, p);
;     };
; #pragma unroll
;     for (int ks = 0; ks < 8; ++ks) { float v[8]; scaled(ks, v); qn[ks] = packed(v); }
; #pragma unroll
;     for (int ks = 8; ks < 10; ++ks) {
;       float x1[8], x2[8]; scaled(ks, x1); scaled(ks + 2, x2);
; #pragma unroll
;       for (int i = 0; i < 8; ++i) {
;         float c, sn; rot_cs(pos, W.rope[8 + 16 * (ks - 8) + 8 * h + i], c, sn);
;         const float a = x1[i] * c - x2[i] * sn, b = x2[i] * c + x1[i] * sn;
;         x1[i] = a; x2[i] = b;
;       }
	v_max_f32_e32 v13, v13, v13
	v_max_f32_e32 v0, v0, v13
	s_waitcnt lgkmcnt(0)
	v_max_f32_e32 v13, v14, v14
	v_max_f32_e32 v12, v12, v13
	v_lshlrev_b32_e32 v13, 2, v20
	v_xor_b32_e32 v13, 4, v13
	v_lshlrev_b32_e32 v14, 2, v21
	ds_bpermute_b32 v13, v13, v0
	v_xor_b32_e32 v14, 4, v14
	ds_bpermute_b32 v14, v14, v12
	global_load_dwordx4 v[30:33], v154, s[52:53] offset:512
	global_load_dwordx4 v[26:29], v154, s[52:53] offset:528
	global_load_dwordx4 v[22:25], v154, s[52:53] offset:640
	global_load_dwordx4 v[18:21], v154, s[52:53] offset:656
	s_bfe_i32 s8, s15, 0x1c0000
	s_waitcnt lgkmcnt(1)
	v_max_f32_e32 v13, v13, v13
	v_max_f32_e32 v0, v0, v13
	s_waitcnt lgkmcnt(0)
	v_max_f32_e32 v13, v14, v14
	v_max_f32_e32 v12, v12, v13
	v_mul_f32_e32 v0, 0x419feb85, v0
	v_mul_f32_e32 v0, v0, v12
	s_mul_i32 s16, s6, 0xc00000
	s_mul_hi_i32 s15, s6, 0xc00000
	s_add_u32 s6, s11, s16
	s_mov_b32 s22, s20
	v_writelane_b32 v255, s22, 23
	s_mul_hi_i32 s19, s4, 0x8604000
	s_mul_i32 s17, s4, 0x9a04000
	v_writelane_b32 v255, s23, 24
	s_waitcnt vmcnt(35)
	v_and_b32_e32 v225, 0xffff0000, v98
	s_waitcnt vmcnt(33)
	v_lshlrev_b32_e32 v216, 16, v110
	v_and_b32_e32 v217, 0xffff0000, v110
	s_waitcnt vmcnt(31)
	v_lshlrev_b32_e32 v208, 16, v119
	s_waitcnt vmcnt(30)
	v_lshlrev_b32_e32 v204, 16, v123
	v_and_b32_e32 v205, 0xffff0000, v123
	s_waitcnt vmcnt(28)
	v_lshlrev_b32_e32 v196, 16, v131
	v_and_b32_e32 v197, 0xffff0000, v131
	s_waitcnt vmcnt(26)
	v_lshlrev_b32_e32 v176, 16, v147
	v_and_b32_e32 v177, 0xffff0000, v147
	s_waitcnt vmcnt(24)
	v_lshlrev_b32_e32 v174, 16, v143
	v_and_b32_e32 v175, 0xffff0000, v143
	s_waitcnt vmcnt(23)
	v_mul_f32_e32 v10, v2, v224
	v_floor_f32_e32 v10, v10
	v_fma_f32 v2, v2, v224, -v10
	v_cos_f32_e32 v150, v2
	v_sin_f32_e32 v156, v2
	v_mul_f32_e32 v2, v3, v224
	v_floor_f32_e32 v2, v2
	v_fma_f32 v2, v3, v224, -v2
	v_cos_f32_e32 v151, v2
	v_sin_f32_e32 v157, v2
	v_mul_f32_e32 v2, v4, v224
	v_floor_f32_e32 v2, v2
	v_fma_f32 v2, v4, v224, -v2
	v_cos_f32_e32 v152, v2
	v_sin_f32_e32 v160, v2
	v_mul_f32_e32 v2, v5, v224
	v_floor_f32_e32 v2, v2
	v_fma_f32 v2, v5, v224, -v2
	v_cos_f32_e32 v153, v2
	v_sin_f32_e32 v161, v2
	s_waitcnt vmcnt(22)
	v_mul_f32_e32 v2, v6, v224
	v_floor_f32_e32 v2, v2
	v_fma_f32 v2, v6, v224, -v2
	v_cos_f32_e32 v158, v2
	v_sin_f32_e32 v164, v2
	v_mul_f32_e32 v2, v7, v224
	v_floor_f32_e32 v2, v2
	v_fma_f32 v2, v7, v224, -v2
	v_cos_f32_e32 v159, v2
	v_sin_f32_e32 v165, v2
	v_mul_f32_e32 v2, v8, v224
	v_floor_f32_e32 v2, v2
	v_fma_f32 v2, v8, v224, -v2
	v_cos_f32_e32 v162, v2
	v_sin_f32_e32 v166, v2
	v_mul_f32_e32 v2, v9, v224
	v_floor_f32_e32 v2, v2
	v_fma_f32 v2, v9, v224, -v2
	v_cos_f32_e32 v163, v2
	v_sin_f32_e32 v167, v2
	global_load_dwordx4 v[14:17], v154, s[52:53] offset:576
	global_load_dwordx4 v[10:13], v154, s[52:53] offset:592
	global_load_dwordx4 v[6:9], v154, s[52:53] offset:704
	global_load_dwordx4 v[2:5], v154, s[52:53] offset:720
	s_waitcnt vmcnt(25)
	v_mul_f32_e32 v154, v168, v224
	v_floor_f32_e32 v154, v154
	v_fma_f32 v220, v168, v224, -v154
	v_mul_f32_e32 v168, v169, v224
	v_floor_f32_e32 v168, v168
	v_fma_f32 v239, v169, v224, -v168
	v_mul_f32_e32 v168, v170, v224
	v_floor_f32_e32 v168, v168
	v_fma_f32 v218, v170, v224, -v168
	v_mul_f32_e32 v168, v171, v224
	v_floor_f32_e32 v168, v168
	v_fma_f32 v238, v171, v224, -v168
	s_waitcnt vmcnt(24)
	v_mul_f32_e32 v168, v102, v224
	v_floor_f32_e32 v168, v168
	v_fma_f32 v219, v102, v224, -v168
	v_mul_f32_e32 v102, v103, v224
	v_floor_f32_e32 v102, v102
	v_fma_f32 v221, v103, v224, -v102
	v_lshlrev_b32_e32 v102, 16, v145
	v_and_b32_e32 v103, 0xffff0000, v145
	v_lshlrev_b32_e32 v170, 16, v144
	v_and_b32_e32 v171, 0xffff0000, v144
	v_lshlrev_b32_e32 v180, 16, v146
	v_and_b32_e32 v181, 0xffff0000, v146
	v_lshlrev_b32_e32 v178, 16, v142
	v_and_b32_e32 v179, 0xffff0000, v142
	v_lshlrev_b32_e32 v146, 16, v137
	v_and_b32_e32 v147, 0xffff0000, v137
	v_lshlrev_b32_e32 v184, 16, v136
	v_and_b32_e32 v185, 0xffff0000, v136
	v_lshlrev_b32_e32 v188, 16, v135
	v_and_b32_e32 v189, 0xffff0000, v135
	v_lshlrev_b32_e32 v192, 16, v134
	v_and_b32_e32 v193, 0xffff0000, v134
	v_lshlrev_b32_e32 v142, 16, v133
	v_and_b32_e32 v143, 0xffff0000, v133
	v_lshlrev_b32_e32 v144, 16, v132
	v_and_b32_e32 v145, 0xffff0000, v132
	v_lshlrev_b32_e32 v198, 16, v130
	v_and_b32_e32 v199, 0xffff0000, v130
	v_lshlrev_b32_e32 v134, 16, v125
	v_and_b32_e32 v135, 0xffff0000, v125
	v_lshlrev_b32_e32 v136, 16, v124
	v_and_b32_e32 v137, 0xffff0000, v124
	v_lshlrev_b32_e32 v206, 16, v122
	v_and_b32_e32 v207, 0xffff0000, v122
	v_lshlrev_b32_e32 v130, 16, v121
	v_and_b32_e32 v131, 0xffff0000, v121
	v_lshlrev_b32_e32 v132, 16, v120
	v_and_b32_e32 v133, 0xffff0000, v120
	v_and_b32_e32 v209, 0xffff0000, v119
	v_lshlrev_b32_e32 v210, 16, v118
	v_and_b32_e32 v211, 0xffff0000, v118
	v_lshlrev_b32_e32 v122, 16, v113
	v_and_b32_e32 v123, 0xffff0000, v113
	v_lshlrev_b32_e32 v124, 16, v112
	v_and_b32_e32 v125, 0xffff0000, v112
	v_lshlrev_b32_e32 v112, 16, v111
	v_and_b32_e32 v113, 0xffff0000, v111
	v_lshlrev_b32_e32 v110, 16, v109
	v_and_b32_e32 v111, 0xffff0000, v109
	v_lshlrev_b32_e32 v118, 16, v108
	v_and_b32_e32 v119, 0xffff0000, v108
	v_lshlrev_b32_e32 v108, 16, v107
	v_and_b32_e32 v109, 0xffff0000, v107
	v_lshlrev_b32_e32 v120, 16, v106
	v_and_b32_e32 v121, 0xffff0000, v106
	v_lshlrev_b32_e32 v106, 16, v101
	v_and_b32_e32 v107, 0xffff0000, v101
	v_mul_f32_e32 v101, v104, v224
	v_floor_f32_e32 v101, v101
	v_fma_f32 v227, v104, v224, -v101
	v_mul_f32_e32 v101, v105, v224
	v_floor_f32_e32 v101, v101
	v_fma_f32 v230, v105, v224, -v101
	v_lshlrev_b32_e32 v224, 16, v98
	v_lshlrev_b32_e32 v168, 16, v149
	v_and_b32_e32 v169, 0xffff0000, v149
; DI float bflo(u32 v) { return __uint_as_float(v << 16); }
; DI float bfhi(u32 v) { return __uint_as_float(v & 0xffff0000u); }
; DI float shx(float v, int k) { return __int_as_float(__builtin_amdgcn_ds_bpermute((lane_id_l() ^ k) << 2, __float_as_int(v))); }
; DI void mla_attn_item(const WsPtrs& W, const float* pgq, const float* pgk, int item, unsigned char* smem) {
;     ...
;     float ss = 0.f;
; #pragma unroll
;     for (int ks = 0; ks < 12; ++ks) {
;       float a;
;       a = bflo(raw[ks].x); ss += a * a; a = bfhi(raw[ks].x); ss += a * a; a = bflo(raw[ks].y); ss += a * a; a = bfhi(raw[ks].y); ss += a * a;
;       a = bflo(raw[ks].z); ss += a * a; a = bfhi(raw[ks].z); ss += a * a; a = bflo(raw[ks].w); ss += a * a; a = bfhi(raw[ks].w); ss += a * a;
;     }
;     ss += shx(ss, 32);
	v_lshlrev_b32_e32 v172, 16, v148
	v_and_b32_e32 v173, 0xffff0000, v148
	v_lshlrev_b32_e32 v148, 16, v141
	v_and_b32_e32 v149, 0xffff0000, v141
	v_lshlrev_b32_e32 v186, 16, v140
	v_and_b32_e32 v187, 0xffff0000, v140
	v_lshlrev_b32_e32 v190, 16, v139
	v_and_b32_e32 v191, 0xffff0000, v139
	v_lshlrev_b32_e32 v194, 16, v138
	v_and_b32_e32 v195, 0xffff0000, v138
	v_lshlrev_b32_e32 v138, 16, v129
	v_and_b32_e32 v139, 0xffff0000, v129
	v_lshlrev_b32_e32 v140, 16, v128
	v_and_b32_e32 v141, 0xffff0000, v128
	v_lshlrev_b32_e32 v200, 16, v127
	v_and_b32_e32 v201, 0xffff0000, v127
	v_lshlrev_b32_e32 v202, 16, v126
	v_and_b32_e32 v203, 0xffff0000, v126
	v_lshlrev_b32_e32 v126, 16, v117
	v_and_b32_e32 v127, 0xffff0000, v117
	v_lshlrev_b32_e32 v128, 16, v116
	v_and_b32_e32 v129, 0xffff0000, v116
	v_lshlrev_b32_e32 v116, 16, v99
	v_and_b32_e32 v117, 0xffff0000, v99
	v_pk_mul_f32 v[98:99], v[224:225], v[224:225]
	v_lshlrev_b32_e32 v212, 16, v115
	v_and_b32_e32 v213, 0xffff0000, v115
	v_lshlrev_b32_e32 v214, 16, v114
	v_and_b32_e32 v215, 0xffff0000, v114
	v_lshlrev_b32_e32 v114, 16, v100
	v_and_b32_e32 v115, 0xffff0000, v100
	v_add_f32_e32 v100, v99, v98
	v_pk_mul_f32 v[98:99], v[116:117], v[116:117]
	v_cos_f32_e32 v154, v220
	v_add_f32_e32 v98, v98, v100
	v_add_f32_e32 v100, v99, v98
	v_pk_mul_f32 v[98:99], v[114:115], v[114:115]
	v_sin_f32_e32 v101, v239
	v_add_f32_e32 v98, v98, v100
	v_add_f32_e32 v100, v99, v98
	v_pk_mul_f32 v[98:99], v[106:107], v[106:107]
	v_sin_f32_e32 v105, v238
	v_add_f32_e32 v98, v98, v100
	v_add_f32_e32 v100, v99, v98
	v_pk_mul_f32 v[98:99], v[120:121], v[120:121]
	s_nop 0
	v_add_f32_e32 v98, v98, v100
	v_add_f32_e32 v100, v99, v98
	v_pk_mul_f32 v[98:99], v[108:109], v[108:109]
	s_nop 0
	v_add_f32_e32 v98, v98, v100
	v_add_f32_e32 v100, v99, v98
	v_pk_mul_f32 v[98:99], v[118:119], v[118:119]
	s_nop 0
	v_add_f32_e32 v98, v98, v100
	v_add_f32_e32 v100, v99, v98
	v_pk_mul_f32 v[98:99], v[110:111], v[110:111]
	s_nop 0
	v_add_f32_e32 v98, v98, v100
	v_add_f32_e32 v100, v99, v98
	v_pk_mul_f32 v[98:99], v[216:217], v[216:217]
	s_nop 0
	v_add_f32_e32 v98, v98, v100
	v_add_f32_e32 v100, v99, v98
	v_pk_mul_f32 v[98:99], v[112:113], v[112:113]
	s_nop 0
	v_add_f32_e32 v98, v98, v100
	v_add_f32_e32 v100, v99, v98
	v_pk_mul_f32 v[98:99], v[124:125], v[124:125]
	s_nop 0
	v_add_f32_e32 v98, v98, v100
	v_add_f32_e32 v100, v99, v98
	v_pk_mul_f32 v[98:99], v[122:123], v[122:123]
	s_nop 0
	v_add_f32_e32 v98, v98, v100
	v_add_f32_e32 v100, v99, v98
	v_pk_mul_f32 v[98:99], v[214:215], v[214:215]
	s_nop 0
	v_add_f32_e32 v98, v98, v100
	v_add_f32_e32 v100, v99, v98
	v_pk_mul_f32 v[98:99], v[212:213], v[212:213]
	s_nop 0
	v_add_f32_e32 v98, v98, v100
	v_add_f32_e32 v100, v99, v98
	v_pk_mul_f32 v[98:99], v[128:129], v[128:129]
	s_nop 0
	v_add_f32_e32 v98, v98, v100
	v_add_f32_e32 v100, v99, v98
	v_pk_mul_f32 v[98:99], v[126:127], v[126:127]
	s_nop 0
	v_add_f32_e32 v98, v98, v100
	v_add_f32_e32 v100, v99, v98
	v_pk_mul_f32 v[98:99], v[210:211], v[210:211]
	s_nop 0
	v_add_f32_e32 v98, v98, v100
	v_add_f32_e32 v100, v99, v98
	v_pk_mul_f32 v[98:99], v[208:209], v[208:209]
	s_nop 0
	v_add_f32_e32 v98, v98, v100
	v_add_f32_e32 v100, v99, v98
	v_pk_mul_f32 v[98:99], v[132:133], v[132:133]
	s_nop 0
	v_add_f32_e32 v98, v98, v100
	v_add_f32_e32 v100, v99, v98
	v_pk_mul_f32 v[98:99], v[130:131], v[130:131]
	s_nop 0
	v_add_f32_e32 v98, v98, v100
	v_add_f32_e32 v100, v99, v98
	v_pk_mul_f32 v[98:99], v[206:207], v[206:207]
	s_nop 0
	v_add_f32_e32 v98, v98, v100
	v_add_f32_e32 v100, v99, v98
	v_pk_mul_f32 v[98:99], v[204:205], v[204:205]
	s_nop 0
	v_add_f32_e32 v98, v98, v100
	v_add_f32_e32 v100, v99, v98
	v_pk_mul_f32 v[98:99], v[136:137], v[136:137]
	s_nop 0
	v_add_f32_e32 v98, v98, v100
	v_add_f32_e32 v100, v99, v98
	v_pk_mul_f32 v[98:99], v[134:135], v[134:135]
	s_nop 0
	v_add_f32_e32 v98, v98, v100
	v_add_f32_e32 v100, v99, v98
	v_pk_mul_f32 v[98:99], v[202:203], v[202:203]
	s_nop 0
	v_add_f32_e32 v98, v98, v100
	v_add_f32_e32 v100, v99, v98
	v_pk_mul_f32 v[98:99], v[200:201], v[200:201]
	s_nop 0
	v_add_f32_e32 v98, v98, v100
	v_add_f32_e32 v100, v99, v98
	v_pk_mul_f32 v[98:99], v[140:141], v[140:141]
	s_nop 0
	v_add_f32_e32 v98, v98, v100
	v_add_f32_e32 v100, v99, v98
	v_pk_mul_f32 v[98:99], v[138:139], v[138:139]
	s_nop 0
	v_add_f32_e32 v98, v98, v100
	v_add_f32_e32 v100, v99, v98
	v_pk_mul_f32 v[98:99], v[198:199], v[198:199]
	s_nop 0
	v_add_f32_e32 v98, v98, v100
	v_add_f32_e32 v100, v99, v98
	v_pk_mul_f32 v[98:99], v[196:197], v[196:197]
	s_nop 0
	v_add_f32_e32 v98, v98, v100
	v_add_f32_e32 v100, v99, v98
	v_pk_mul_f32 v[98:99], v[144:145], v[144:145]
	s_nop 0
	v_add_f32_e32 v98, v98, v100
	v_add_f32_e32 v100, v99, v98
	v_pk_mul_f32 v[98:99], v[142:143], v[142:143]
	s_nop 0
	v_add_f32_e32 v98, v98, v100
	v_add_f32_e32 v100, v99, v98
	v_pk_mul_f32 v[98:99], v[194:195], v[194:195]
	s_nop 0
	v_add_f32_e32 v98, v98, v100
	v_add_f32_e32 v100, v99, v98
	v_pk_mul_f32 v[98:99], v[190:191], v[190:191]
	s_nop 0
	v_add_f32_e32 v98, v98, v100
	v_add_f32_e32 v100, v99, v98
	v_pk_mul_f32 v[98:99], v[186:187], v[186:187]
	s_nop 0
	v_add_f32_e32 v98, v98, v100
	v_add_f32_e32 v100, v99, v98
	v_pk_mul_f32 v[98:99], v[148:149], v[148:149]
	s_nop 0
	v_add_f32_e32 v98, v98, v100
	v_add_f32_e32 v100, v99, v98
	v_pk_mul_f32 v[98:99], v[180:181], v[180:181]
	s_nop 0
	v_add_f32_e32 v98, v98, v100
	v_add_f32_e32 v100, v99, v98
	v_pk_mul_f32 v[98:99], v[176:177], v[176:177]
	s_nop 0
	v_add_f32_e32 v98, v98, v100
	v_add_f32_e32 v100, v99, v98
	v_pk_mul_f32 v[98:99], v[172:173], v[172:173]
	s_nop 0
	v_add_f32_e32 v98, v98, v100
	v_add_f32_e32 v100, v99, v98
	v_pk_mul_f32 v[98:99], v[168:169], v[168:169]
	s_nop 0
	v_add_f32_e32 v98, v98, v100
	v_add_f32_e32 v100, v99, v98
	v_pk_mul_f32 v[98:99], v[192:193], v[192:193]
	s_nop 0
	v_add_f32_e32 v98, v98, v100
	v_add_f32_e32 v100, v99, v98
	v_pk_mul_f32 v[98:99], v[188:189], v[188:189]
	s_nop 0
	v_add_f32_e32 v98, v98, v100
	v_add_f32_e32 v100, v99, v98
	v_pk_mul_f32 v[98:99], v[184:185], v[184:185]
	s_nop 0
	v_add_f32_e32 v98, v98, v100
	v_add_f32_e32 v100, v99, v98
	v_pk_mul_f32 v[98:99], v[146:147], v[146:147]
	s_nop 0
	v_add_f32_e32 v98, v98, v100
	v_add_f32_e32 v100, v99, v98
	v_pk_mul_f32 v[98:99], v[178:179], v[178:179]
	s_nop 0
	v_add_f32_e32 v98, v98, v100
	v_add_f32_e32 v100, v99, v98
	v_pk_mul_f32 v[98:99], v[174:175], v[174:175]
	s_nop 0
	v_add_f32_e32 v98, v98, v100
	v_add_f32_e32 v100, v99, v98
	v_pk_mul_f32 v[98:99], v[170:171], v[170:171]
	s_nop 0
	v_add_f32_e32 v98, v98, v100
	v_add_f32_e32 v100, v99, v98
	v_pk_mul_f32 v[98:99], v[102:103], v[102:103]
	s_nop 0
	v_add_f32_e32 v98, v98, v100
	v_add_f32_e32 v99, v99, v98
	ds_bpermute_b32 v104, v155, v99
	v_sin_f32_e32 v100, v220
	v_cos_f32_e32 v98, v218
	v_cos_f32_e32 v155, v239
	s_waitcnt lgkmcnt(0)
; DI u32 pack2(float a, float b) { f2_t v = {a, b}; bf2_t r = __builtin_convertvector(v, bf2_t); return __builtin_bit_cast(u32, r); }
; DI float bflo(u32 v) { return __uint_as_float(v << 16); }
; DI float bfhi(u32 v) { return __uint_as_float(v & 0xffff0000u); }
; DI float shx(float v, int k) { return __int_as_float(__builtin_amdgcn_ds_bpermute((lane_id_l() ^ k) << 2, __float_as_int(v))); }
; DI void mla_attn_item(const WsPtrs& W, const float* pgq, const float* pgk, int item, unsigned char* smem) {
;     ...
;     ss += shx(ss, 32);
;     const float sc = rsqrtf(ss * (1.f / 192.f) + EPSV) * (0.07216878364870322f * LOG2E);
;     const float pos = (float)(q0 + r);
;     auto scaled = [&](int ks, float (&v)[8]) __attribute__((always_inline)) {
;       const f32x4 g0 = *(const f32x4*)(pgq + 16 * ks + 8 * h), g1 = *(const f32x4*)(pgq + 16 * ks + 8 * h + 4);
;       v[0] = bflo(raw[ks].x) * sc * g0.x; v[1] = bfhi(raw[ks].x) * sc * g0.y; v[2] = bflo(raw[ks].y) * sc * g0.z; v[3] = bfhi(raw[ks].y) * sc * g0.w;
;       v[4] = bflo(raw[ks].z) * sc * g1.x; v[5] = bfhi(raw[ks].z) * sc * g1.y; v[6] = bflo(raw[ks].w) * sc * g1.z; v[7] = bfhi(raw[ks].w) * sc * g1.w;
;     };
;     auto packed = [&](const float (&v)[8]) __attribute__((always_inline)) {
;       u32x4 p; p.x = pack2(v[0], v[1]); p.y = pack2(v[2], v[3]); p.z = pack2(v[4], v[5]); p.w = pack2(v[6], v[7]);
;       return __builtin_bit_cast(bf16x8, p);
;     };
; #pragma unroll
;     for (int ks = 0; ks < 8; ++ks) { float v[8]; scaled(ks, v); qn[ks] = packed(v); }
; #pragma unroll
;     for (int ks = 8; ks < 10; ++ks) {
;       float x1[8], x2[8]; scaled(ks, x1); scaled(ks + 2, x2);
; #pragma unroll
;       for (int i = 0; i < 8; ++i) {
;         float c, sn; rot_cs(pos, W.rope[8 + 16 * (ks - 8) + 8 * h + i], c, sn);
;         const float a = x1[i] * c - x2[i] * sn, b = x2[i] * c + x1[i] * sn;
;         x1[i] = a; x2[i] = b;
;       }
;       qn[ks] = packed(x1); qn[ks + 2] = packed(x2);
;     }
;   }
;   if (M <= 56.f)
	v_add_f32_e32 v99, v99, v104
	v_fmamk_f32 v99, v99, 0x3baaaaab, v228
	v_mul_f32_e32 v104, 0x4b800000, v99
	v_cmp_gt_f32_e32 vcc, s7, v99
	s_mov_b32 s7, 0x3f828f5c
	s_nop 0
	v_cndmask_b32_e32 v99, v99, v104, vcc
	v_rsq_f32_e32 v220, v99
	v_sin_f32_e32 v104, v218
	v_cos_f32_e32 v99, v238
	v_mul_f32_e32 v218, 0x45800000, v220
	v_cndmask_b32_e32 v218, v220, v218, vcc
	v_mul_f32_e32 v226, 0x3dd53b94, v218
	v_pk_mul_f32 v[224:225], v[226:227], v[224:225] op_sel_hi:[0,1]
	s_waitcnt vmcnt(22)
	v_pk_mul_f32 v[224:225], v[94:95], v[224:225]
	v_pk_mul_f32 v[94:95], v[226:227], v[116:117] op_sel_hi:[0,1]
	v_pk_mul_f32 v[114:115], v[226:227], v[114:115] op_sel_hi:[0,1]
	v_pk_mul_f32 v[116:117], v[96:97], v[94:95]
	v_pk_mul_f32 v[90:91], v[90:91], v[114:115]
	v_cvt_pk_bf16_f32 v115, v116, v117
	v_cvt_pk_bf16_f32 v116, v90, v91
	v_pk_mul_f32 v[90:91], v[226:227], v[120:121] op_sel_hi:[0,1]
	s_waitcnt vmcnt(20)
	v_pk_mul_f32 v[86:87], v[86:87], v[90:91]
	v_pk_mul_f32 v[90:91], v[226:227], v[108:109] op_sel_hi:[0,1]
	v_pk_mul_f32 v[88:89], v[88:89], v[90:91]
	v_pk_mul_f32 v[90:91], v[226:227], v[118:119] op_sel_hi:[0,1]
	v_pk_mul_f32 v[82:83], v[82:83], v[90:91]
	v_cos_f32_e32 v218, v219
	v_cvt_pk_bf16_f32 v120, v82, v83
	v_pk_mul_f32 v[82:83], v[226:227], v[216:217] op_sel_hi:[0,1]
	s_waitcnt vmcnt(18)
	v_pk_mul_f32 v[78:79], v[78:79], v[82:83]
	v_pk_mul_f32 v[82:83], v[226:227], v[112:113] op_sel_hi:[0,1]
	v_pk_mul_f32 v[80:81], v[80:81], v[82:83]
	v_pk_mul_f32 v[82:83], v[226:227], v[124:125] op_sel_hi:[0,1]
	v_pk_mul_f32 v[74:75], v[74:75], v[82:83]
	v_sin_f32_e32 v220, v219
	v_cvt_pk_bf16_f32 v124, v74, v75
	v_pk_mul_f32 v[74:75], v[226:227], v[214:215] op_sel_hi:[0,1]
	s_waitcnt vmcnt(16)
	v_pk_mul_f32 v[70:71], v[70:71], v[74:75]
	v_pk_mul_f32 v[74:75], v[226:227], v[212:213] op_sel_hi:[0,1]
	v_pk_mul_f32 v[72:73], v[72:73], v[74:75]
	v_pk_mul_f32 v[74:75], v[226:227], v[128:129] op_sel_hi:[0,1]
	v_pk_mul_f32 v[66:67], v[66:67], v[74:75]
	v_cos_f32_e32 v219, v221
	v_cvt_pk_bf16_f32 v128, v66, v67
	v_pk_mul_f32 v[66:67], v[226:227], v[210:211] op_sel_hi:[0,1]
	s_waitcnt vmcnt(14)
	v_pk_mul_f32 v[62:63], v[62:63], v[66:67]
	v_pk_mul_f32 v[66:67], v[226:227], v[208:209] op_sel_hi:[0,1]
	v_pk_mul_f32 v[64:65], v[64:65], v[66:67]
	v_pk_mul_f32 v[66:67], v[226:227], v[132:133] op_sel_hi:[0,1]
	v_pk_mul_f32 v[58:59], v[58:59], v[66:67]
	v_sin_f32_e32 v221, v221
	v_cvt_pk_bf16_f32 v132, v58, v59
	v_pk_mul_f32 v[58:59], v[226:227], v[206:207] op_sel_hi:[0,1]
	s_waitcnt vmcnt(12)
	v_pk_mul_f32 v[54:55], v[54:55], v[58:59]
	v_pk_mul_f32 v[58:59], v[226:227], v[204:205] op_sel_hi:[0,1]
	v_pk_mul_f32 v[56:57], v[56:57], v[58:59]
	v_pk_mul_f32 v[58:59], v[226:227], v[136:137] op_sel_hi:[0,1]
	v_pk_mul_f32 v[50:51], v[50:51], v[58:59]
	v_sin_f32_e32 v96, v227
	v_cvt_pk_bf16_f32 v136, v50, v51
	v_pk_mul_f32 v[50:51], v[226:227], v[202:203] op_sel_hi:[0,1]
	s_waitcnt vmcnt(10)
	v_pk_mul_f32 v[46:47], v[46:47], v[50:51]
	v_pk_mul_f32 v[50:51], v[226:227], v[200:201] op_sel_hi:[0,1]
	v_pk_mul_f32 v[48:49], v[48:49], v[50:51]
	v_pk_mul_f32 v[50:51], v[226:227], v[140:141] op_sel_hi:[0,1]
	v_pk_mul_f32 v[42:43], v[42:43], v[50:51]
	v_sin_f32_e32 v97, v230
	v_cvt_pk_bf16_f32 v140, v42, v43
	v_pk_mul_f32 v[42:43], v[226:227], v[198:199] op_sel_hi:[0,1]
	s_waitcnt vmcnt(8)
	v_pk_mul_f32 v[38:39], v[38:39], v[42:43]
	v_pk_mul_f32 v[42:43], v[226:227], v[196:197] op_sel_hi:[0,1]
	v_pk_mul_f32 v[40:41], v[40:41], v[42:43]
	v_pk_mul_f32 v[42:43], v[226:227], v[144:145] op_sel_hi:[0,1]
	v_pk_mul_f32 v[34:35], v[34:35], v[42:43]
	v_pk_mul_f32 v[66:67], v[226:227], v[130:131] op_sel_hi:[0,1]
	v_cvt_pk_bf16_f32 v144, v34, v35
	v_pk_mul_f32 v[34:35], v[226:227], v[194:195] op_sel_hi:[0,1]
	s_waitcnt vmcnt(7)
	v_pk_mul_f32 v[30:31], v[30:31], v[34:35]
	v_pk_mul_f32 v[34:35], v[226:227], v[190:191] op_sel_hi:[0,1]
	v_pk_mul_f32 v[32:33], v[32:33], v[34:35]
	v_pk_mul_f32 v[34:35], v[226:227], v[186:187] op_sel_hi:[0,1]
	s_waitcnt vmcnt(6)
	v_pk_mul_f32 v[26:27], v[26:27], v[34:35]
	v_pk_mul_f32 v[34:35], v[226:227], v[148:149] op_sel_hi:[0,1]
	v_pk_mul_f32 v[28:29], v[28:29], v[34:35]
	v_pk_mul_f32 v[34:35], v[226:227], v[192:193] op_sel_hi:[0,1]
	s_waitcnt vmcnt(5)
	v_pk_mul_f32 v[22:23], v[22:23], v[34:35]
	v_pk_mul_f32 v[34:35], v[226:227], v[188:189] op_sel_hi:[0,1]
	v_pk_mul_f32 v[24:25], v[24:25], v[34:35]
	v_pk_mul_f32 v[34:35], v[226:227], v[184:185] op_sel_hi:[0,1]
	s_waitcnt vmcnt(4)
	v_pk_mul_f32 v[18:19], v[18:19], v[34:35]
	v_pk_mul_f32 v[34:35], v[226:227], v[146:147] op_sel_hi:[0,1]
	v_pk_mul_f32 v[20:21], v[20:21], v[34:35]
	v_pk_mul_f32 v[34:35], v[156:157], v[30:31]
	v_cos_f32_e32 v94, v227
	v_pk_fma_f32 v[34:35], v[150:151], v[22:23], v[34:35]
	v_pk_mul_f32 v[22:23], v[156:157], v[22:23]
	v_cos_f32_e32 v95, v230
	v_pk_fma_f32 v[22:23], v[150:151], v[30:31], v[22:23] neg_lo:[0,0,1] neg_hi:[0,0,1]
	v_pk_mul_f32 v[30:31], v[160:161], v[32:33]
	v_pk_mul_f32 v[60:61], v[60:61], v[66:67]
	v_pk_fma_f32 v[30:31], v[152:153], v[24:25], v[30:31]
	v_pk_mul_f32 v[24:25], v[160:161], v[24:25]
	v_fma_f32 v66, v0, s7, 1.0
	v_pk_fma_f32 v[24:25], v[152:153], v[32:33], v[24:25] neg_lo:[0,0,1] neg_hi:[0,0,1]
	v_pk_mul_f32 v[32:33], v[164:165], v[26:27]
	s_mov_b32 s7, 0x42600000
	v_pk_fma_f32 v[32:33], v[158:159], v[18:19], v[32:33]
	v_pk_mul_f32 v[18:19], v[164:165], v[18:19]
	v_cmp_ge_f32_e32 vcc, s7, v66
	v_pk_fma_f32 v[18:19], v[158:159], v[26:27], v[18:19] neg_lo:[0,0,1] neg_hi:[0,0,1]
	s_addc_u32 s7, s12, s15
	v_cvt_pk_bf16_f32 v148, v18, v19
	v_pk_mul_f32 v[18:19], v[226:227], v[180:181] op_sel_hi:[0,1]
	s_waitcnt vmcnt(3)
;     ...
;   u32x4 rk[NKL], rv[2];
;   u32 koff[NKL]; int klds[NKL];
; #pragma unroll
;   for (int i = 0; i < NKL; ++i) { int c = tid + NTHR * i; int row = c / KCH, kc = c % KCH; koff[i] = (u32)(row * ldk + 8 * kc) * 2u; klds[i] = row * KST + 8 * kc; }
;   const u32 voff = (u32)((tid >> 3) * 4096 + 8 * (tid & 7)) * 2u;
;   const int vlds = 64 * KST + (tid >> 3) * 72 + 8 * (tid & 7);
;   auto gload = [&](int k0) __attribute__((always_inline)) {
;     const char* kb = (const char*)Kg + (size_t)k0 * ldk * 2;
; #pragma unroll
;     for (int i = 0; i < NKL; ++i) rk[i] = *(const u32x4*)(kb + koff[i]);
;     const char* vb = (const char*)VTg + (size_t)k0 * 2;
; #pragma unroll
;     for (int i = 0; i < 2; ++i) rv[i] = *(const u32x4*)(vb + (size_t)i * 64 * 4096 * 2 + voff);
;   };
;   auto lstore = [&](int b) __attribute__((always_inline)) {
;     u16* St = S0 + b * STG;
; #pragma unroll
;     for (int i = 0; i < NKL; ++i) *(u32x4*)(St + klds[i]) = rk[i];
; #pragma unroll
;     for (int i = 0; i < 2; ++i) *(u32x4*)(St + vlds + i * 64 * 72) = rv[i];
;   };
;   gload(kt0 * 64);
;   __syncthreads();
; DI void mla_attn_item(const WsPtrs& W, const float* pgq, const float* pgk, int item, unsigned char* smem) {
;     ...
;       for (int i = 0; i < 8; ++i) {
;         float c, sn; rot_cs(pos, W.rope[8 + 16 * (ks - 8) + 8 * h + i], c, sn);
;         const float a = x1[i] * c - x2[i] * sn, b = x2[i] * c + x1[i] * sn;
;         x1[i] = a; x2[i] = b;
;       }
;       qn[ks] = packed(x1); qn[ks + 2] = packed(x2);
;     }
;   }
;   if (M <= 56.f)
;     attn_core<192, 192, 1>(W.QC + (tokb + q0) * 1536 + hh * 192, 1536, W.KC + tokb * 1536 + hh * 192, 1536,
;                            W.CVT + (size_t)bh * 128 * 4096, 0, q0, M, o, l, smem, 0, 64, true, qn);
	v_pk_mul_f32 v[14:15], v[14:15], v[18:19]
	v_pk_mul_f32 v[18:19], v[226:227], v[176:177] op_sel_hi:[0,1]
	v_pk_mul_f32 v[16:17], v[16:17], v[18:19]
	v_pk_mul_f32 v[18:19], v[226:227], v[172:173] op_sel_hi:[0,1]
	s_waitcnt vmcnt(2)
	v_pk_mul_f32 v[10:11], v[10:11], v[18:19]
	v_pk_mul_f32 v[18:19], v[226:227], v[168:169] op_sel_hi:[0,1]
	v_pk_mul_f32 v[12:13], v[12:13], v[18:19]
	v_pk_mul_f32 v[18:19], v[226:227], v[178:179] op_sel_hi:[0,1]
	s_waitcnt vmcnt(1)
	v_pk_mul_f32 v[6:7], v[6:7], v[18:19]
	v_pk_mul_f32 v[18:19], v[226:227], v[174:175] op_sel_hi:[0,1]
	v_pk_mul_f32 v[8:9], v[8:9], v[18:19]
	v_pk_mul_f32 v[18:19], v[226:227], v[170:171] op_sel_hi:[0,1]
	s_waitcnt vmcnt(0)
	v_pk_mul_f32 v[2:3], v[2:3], v[18:19]
	v_pk_mul_f32 v[18:19], v[226:227], v[102:103] op_sel_hi:[0,1]
	v_pk_mul_f32 v[4:5], v[4:5], v[18:19]
	v_pk_mul_f32 v[18:19], v[100:101], v[14:15]
	s_add_u32 s6, s6, s20
	v_pk_fma_f32 v[18:19], v[154:155], v[6:7], v[18:19]
	v_pk_mul_f32 v[6:7], v[100:101], v[6:7]
	v_pk_mul_f32 v[26:27], v[166:167], v[28:29]
	v_pk_fma_f32 v[6:7], v[154:155], v[14:15], v[6:7] neg_lo:[0,0,1] neg_hi:[0,0,1]
	v_pk_mul_f32 v[14:15], v[104:105], v[16:17]
	s_addc_u32 s7, s7, 0
	v_pk_fma_f32 v[14:15], v[98:99], v[8:9], v[14:15]
	v_pk_mul_f32 v[8:9], v[104:105], v[8:9]
	s_ashr_i32 s9, s8, 31
	v_pk_fma_f32 v[8:9], v[98:99], v[16:17], v[8:9] neg_lo:[0,0,1] neg_hi:[0,0,1]
	v_pk_mul_f32 v[16:17], v[220:221], v[10:11]
	v_pk_mul_f32 v[106:107], v[226:227], v[106:107] op_sel_hi:[0,1]
	v_pk_fma_f32 v[16:17], v[218:219], v[2:3], v[16:17]
	v_pk_mul_f32 v[2:3], v[220:221], v[2:3]
	v_pk_mul_f32 v[90:91], v[226:227], v[110:111] op_sel_hi:[0,1]
	v_pk_fma_f32 v[2:3], v[218:219], v[10:11], v[2:3] neg_lo:[0,0,1] neg_hi:[0,0,1]
	v_pk_mul_f32 v[10:11], v[96:97], v[12:13]
	v_pk_mul_f32 v[82:83], v[226:227], v[122:123] op_sel_hi:[0,1]
	v_pk_mul_f32 v[74:75], v[226:227], v[126:127] op_sel_hi:[0,1]
	v_pk_mul_f32 v[58:59], v[226:227], v[134:135] op_sel_hi:[0,1]
	v_pk_mul_f32 v[50:51], v[226:227], v[138:139] op_sel_hi:[0,1]
	v_pk_mul_f32 v[42:43], v[226:227], v[142:143] op_sel_hi:[0,1]
	v_pk_fma_f32 v[26:27], v[162:163], v[20:21], v[26:27]
	v_pk_mul_f32 v[20:21], v[166:167], v[20:21]
	v_pk_fma_f32 v[10:11], v[94:95], v[4:5], v[10:11]
	v_pk_mul_f32 v[4:5], v[96:97], v[4:5]
	s_lshl_b64 s[8:9], s[8:9], 20
	v_pk_mul_f32 v[92:93], v[92:93], v[106:107]
	v_pk_mul_f32 v[84:85], v[84:85], v[90:91]
	v_pk_mul_f32 v[76:77], v[76:77], v[82:83]
	v_pk_mul_f32 v[68:69], v[68:69], v[74:75]
	v_pk_mul_f32 v[52:53], v[52:53], v[58:59]
	v_pk_mul_f32 v[44:45], v[44:45], v[50:51]
	v_pk_mul_f32 v[36:37], v[36:37], v[42:43]
	v_pk_fma_f32 v[20:21], v[162:163], v[28:29], v[20:21] neg_lo:[0,0,1] neg_hi:[0,0,1]
	v_pk_fma_f32 v[4:5], v[94:95], v[12:13], v[4:5] neg_lo:[0,0,1] neg_hi:[0,0,1]
	s_add_u32 s8, s5, s8
	v_cvt_pk_bf16_f32 v114, v224, v225
	v_cvt_pk_bf16_f32 v117, v92, v93
	v_cvt_pk_bf16_f32 v118, v86, v87
	v_cvt_pk_bf16_f32 v119, v88, v89
	v_cvt_pk_bf16_f32 v121, v84, v85
	v_cvt_pk_bf16_f32 v122, v78, v79
	v_cvt_pk_bf16_f32 v123, v80, v81
	v_cvt_pk_bf16_f32 v125, v76, v77
	v_cvt_pk_bf16_f32 v126, v70, v71
	v_cvt_pk_bf16_f32 v127, v72, v73
	v_cvt_pk_bf16_f32 v129, v68, v69
	v_cvt_pk_bf16_f32 v130, v62, v63
	v_cvt_pk_bf16_f32 v131, v64, v65
	v_cvt_pk_bf16_f32 v133, v60, v61
	v_cvt_pk_bf16_f32 v134, v54, v55
	v_cvt_pk_bf16_f32 v135, v56, v57
	v_cvt_pk_bf16_f32 v137, v52, v53
	v_cvt_pk_bf16_f32 v138, v46, v47
	v_cvt_pk_bf16_f32 v139, v48, v49
	v_cvt_pk_bf16_f32 v141, v44, v45
	v_cvt_pk_bf16_f32 v142, v38, v39
	v_cvt_pk_bf16_f32 v143, v40, v41
	v_cvt_pk_bf16_f32 v145, v36, v37
	v_cvt_pk_bf16_f32 v146, v22, v23
	v_cvt_pk_bf16_f32 v147, v24, v25
	v_cvt_pk_bf16_f32 v149, v20, v21
	v_cvt_pk_bf16_f32 v150, v34, v35
	v_cvt_pk_bf16_f32 v151, v30, v31
	v_cvt_pk_bf16_f32 v152, v32, v33
	v_cvt_pk_bf16_f32 v153, v26, v27
	v_cvt_pk_bf16_f32 v154, v6, v7
	v_cvt_pk_bf16_f32 v155, v8, v9
	v_cvt_pk_bf16_f32 v156, v2, v3
	v_cvt_pk_bf16_f32 v157, v4, v5
	v_cvt_pk_bf16_f32 v158, v18, v19
	v_cvt_pk_bf16_f32 v159, v14, v15
	v_cvt_pk_bf16_f32 v160, v16, v17
	v_cvt_pk_bf16_f32 v161, v10, v11
	s_addc_u32 s9, s14, s9
	s_mul_i32 s20, s4, 0x8604000
	s_mul_hi_i32 s14, s4, 0x9a04000
	s_and_saveexec_b64 s[4:5], vcc
	s_xor_b64 s[4:5], exec, s[4:5]
	s_cbranch_execz .LBB0_597
	v_mov_b32_e32 v23, v250
	s_mov_b32 s22, 0x2aaaaaab
	s_movk_i32 s21, 0x600
	v_mul_hi_i32 v0, v23, s22
	v_lshrrev_b32_e32 v2, 31, v0
	v_ashrrev_i32_e32 v0, 2, v0
	v_add_u32_e32 v25, v0, v2
	v_mul_lo_u32 v0, v25, 24
	v_sub_u32_e32 v0, v23, v0
	v_mul_lo_u32 v2, v25, s21
	v_lshl_add_u32 v22, v0, 3, v2
	v_add_u32_e32 v2, 0x200, v23
	v_mul_hi_i32 v3, v2, s22
	v_lshrrev_b32_e32 v4, 31, v3
	v_ashrrev_i32_e32 v3, 2, v3
	v_add_u32_e32 v29, v3, v4
	v_mul_lo_u32 v3, v29, 24
	v_sub_u32_e32 v2, v2, v3
	v_mul_lo_u32 v3, v29, s21
	v_lshl_add_u32 v24, v2, 3, v3
	v_add_u32_e32 v2, 0x400, v23
	v_mul_hi_i32 v3, v2, s22
	v_lshrrev_b32_e32 v4, 31, v3
	v_ashrrev_i32_e32 v3, 2, v3
	v_add_u32_e32 v33, v3, v4
	v_mul_lo_u32 v3, v33, 24
	v_sub_u32_e32 v2, v2, v3
	v_mul_lo_u32 v3, v33, s21
	v_lshl_add_u32 v28, v2, 3, v3
	v_ashrrev_i32_e32 v38, 3, v23
	v_lshlrev_b32_e32 v2, 3, v23
	v_and_b32_e32 v32, 56, v2
	v_lshlrev_b32_e32 v2, 13, v38
	v_lshl_or_b32 v34, v32, 1, v2
	v_mov_b32_e32 v35, v1
	v_lshl_add_u64 v[18:19], s[8:9], 0, v[34:35]
	s_mov_b32 s21, 0x80000
	v_add_co_u32_e32 v36, vcc, s21, v18
	s_add_u32 s22, s6, 0x30000
	v_lshlrev_b32_e32 v0, 1, v22
	v_lshlrev_b32_e32 v26, 1, v24
	v_lshlrev_b32_e32 v30, 1, v28
	v_addc_co_u32_e32 v37, vcc, 0, v19, vcc
	s_addc_u32 s23, s7, 0
	global_load_dwordx4 v[2:5], v0, s[6:7]
	global_load_dwordx4 v[6:9], v26, s[6:7]
	global_load_dwordx4 v[10:13], v30, s[6:7]
	global_load_dwordx4 v[14:17], v34, s[8:9]
	global_load_dwordx4 v[18:21], v[36:37], off
	s_barrier
;     ...
;   u32x4 rk[NKL], rv[2];
;   u32 koff[NKL]; int klds[NKL];
; #pragma unroll
;   for (int i = 0; i < NKL; ++i) { int c = tid + NTHR * i; int row = c / KCH, kc = c % KCH; koff[i] = (u32)(row * ldk + 8 * kc) * 2u; klds[i] = row * KST + 8 * kc; }
;   const u32 voff = (u32)((tid >> 3) * 4096 + 8 * (tid & 7)) * 2u;
;   const int vlds = 64 * KST + (tid >> 3) * 72 + 8 * (tid & 7);
;   auto gload = [&](int k0) __attribute__((always_inline)) {
;     const char* kb = (const char*)Kg + (size_t)k0 * ldk * 2;
; #pragma unroll
;     for (int i = 0; i < NKL; ++i) rk[i] = *(const u32x4*)(kb + koff[i]);
;     const char* vb = (const char*)VTg + (size_t)k0 * 2;
; #pragma unroll
;     for (int i = 0; i < 2; ++i) rv[i] = *(const u32x4*)(vb + (size_t)i * 64 * 4096 * 2 + voff);
;   };
;   auto lstore = [&](int b) __attribute__((always_inline)) {
;     u16* St = S0 + b * STG;
; #pragma unroll
;     for (int i = 0; i < NKL; ++i) *(u32x4*)(St + klds[i]) = rk[i];
; #pragma unroll
;     for (int i = 0; i < 2; ++i) *(u32x4*)(St + vlds + i * 64 * 72) = rv[i];
;   };
;   gload(kt0 * 64);
;   __syncthreads();
;   lstore(0);
;   gload((kt0 + 1) * 64);
;   __syncthreads();
;   const float qpos = (float)(qpos0 + r);
	global_load_dwordx4 v[162:165], v26, s[22:23]
	global_load_dwordx4 v[170:173], v30, s[22:23]
	global_load_dwordx4 v[174:177], v34, s[8:9] offset:128
	global_load_dwordx4 v[166:169], v0, s[22:23]
	global_load_dwordx4 v[178:181], v[36:37], off offset:128
	v_readlane_b32 s22, v255, 25
	s_or_b32 s22, s22, s13
	s_bfe_i32 s23, s22, 0x1001b
	s_bfe_i32 s22, s22, 0x1c0000
	s_lshl_b64 s[22:23], s[22:23], 20
	s_add_u32 s22, s20, s22
	s_addc_u32 s23, s19, s23
	v_and_b32_e32 v39, 31, v23
	v_lshrrev_b32_e32 v23, 2, v23
	v_mov_b32_e32 v192, v34
	v_add_u32_e32 v193, 0x80000, v34
	s_add_u32 s100, s22, s62
	s_addc_u32 s101, s23, s63
	s_add_u32 s100, s100, 0x7046000
	s_addc_u32 s101, s101, 0
	v_readlane_b32 s22, v255, 46
	v_and_b32_e32 v23, 8, v23
	s_movk_i32 s24, 0x48
	s_movk_i32 s26, 0xfac8
	s_add_u32 s22, s22, s17
	v_readlane_b32 s23, v255, 47
	v_mad_u64_u32 v[184:185], s[24:25], v38, s24, v[32:33]
	v_mad_u64_u32 v[186:187], s[24:25], v25, s26, v[22:23]
	s_addc_u32 s23, s23, s14
	v_mad_u64_u32 v[188:189], s[24:25], v29, s26, v[24:25]
	v_mad_u64_u32 v[190:191], s[24:25], v33, s26, v[28:29]
	v_lshl_add_u32 v22, v186, 1, 64
	s_add_u32 s22, s22, s16
	v_mov_b32_e32 v27, v1
	v_mov_b32_e32 v31, v1
	v_xor_b32_e32 v66, 0x80000000, v66
	v_mul_u32_u24_e32 v40, 0xc8, v39
	v_lshl_add_u32 v32, v184, 1, 64
	v_lshl_add_u32 v24, v188, 1, 64
	v_lshl_add_u32 v25, v190, 1, 64
	s_addc_u32 s23, s23, s15
	v_mov_b32_e32 v185, 0
	s_mov_b32 s21, 0
	v_mov_b32_e32 v67, v66
	v_mov_b32_e32 v68, v66
	v_mov_b32_e32 v69, v66
	v_mov_b32_e32 v70, v66
	v_mov_b32_e32 v71, v66
	v_mov_b32_e32 v72, v66
	v_mov_b32_e32 v73, v66
	v_mov_b32_e32 v74, v66
	v_mov_b32_e32 v75, v66
	s_waitcnt vmcnt(9)
	ds_write_b128 v22, v[2:5]
	s_waitcnt vmcnt(8)
	ds_write_b128 v24, v[6:9]
	s_waitcnt vmcnt(7)
	ds_write_b128 v25, v[10:13]
	s_waitcnt vmcnt(6)
	ds_write_b128 v32, v[14:17] offset:25600
	s_waitcnt vmcnt(5)
	ds_write_b128 v32, v[18:21] offset:34816
	v_lshlrev_b32_e32 v2, 8, v39
	v_mov_b32_e32 v76, v66
	v_mov_b32_e32 v77, v66
	v_mov_b32_e32 v78, v66
	v_mov_b32_e32 v79, v66
	v_mov_b32_e32 v80, v66
	v_mov_b32_e32 v81, v66
	v_mul_u32_u24_e32 v187, 0x190, v39
	v_sub_u32_e32 v189, 0, v2
	v_mov_b32_e32 v194, v0
	v_mov_b32_e32 v195, v26
	v_mov_b32_e32 v196, v30
	v_lshlrev_b32_e32 v0, 1, v40
	v_lshlrev_b32_e32 v191, 1, v23
	v_mov_b32_e32 v50, 0
	v_mov_b32_e32 v51, v185
	v_mov_b32_e32 v52, v185
	v_mov_b32_e32 v53, v185
	v_mov_b32_e32 v54, v185
	v_mov_b32_e32 v55, v185
	v_mov_b32_e32 v56, v185
	v_mov_b32_e32 v57, v185
	v_mov_b32_e32 v58, v185
	v_mov_b32_e32 v59, v185
	v_mov_b32_e32 v60, v185
	v_mov_b32_e32 v61, v185
	v_mov_b32_e32 v62, v185
	v_mov_b32_e32 v63, v185
	v_mov_b32_e32 v64, v185
	v_mov_b32_e32 v65, v185
	v_mov_b32_e32 v34, 0
	v_mov_b32_e32 v35, v185
	v_mov_b32_e32 v36, v185
	v_mov_b32_e32 v37, v185
	v_mov_b32_e32 v38, v185
	v_mov_b32_e32 v39, v185
	v_mov_b32_e32 v40, v185
	v_mov_b32_e32 v41, v185
	v_mov_b32_e32 v42, v185
	v_mov_b32_e32 v43, v185
	v_mov_b32_e32 v44, v185
	v_mov_b32_e32 v45, v185
	v_mov_b32_e32 v46, v185
	v_mov_b32_e32 v47, v185
	v_mov_b32_e32 v48, v185
	v_mov_b32_e32 v49, v185
	v_mov_b32_e32 v18, 0
	v_mov_b32_e32 v19, v185
	v_mov_b32_e32 v20, v185
	v_mov_b32_e32 v21, v185
	v_mov_b32_e32 v22, v185
	v_mov_b32_e32 v23, v185
	v_mov_b32_e32 v24, v185
	v_mov_b32_e32 v25, v185
	v_mov_b32_e32 v26, v185
	v_mov_b32_e32 v27, v185
	v_mov_b32_e32 v28, v185
	v_mov_b32_e32 v29, v185
	v_mov_b32_e32 v30, v185
	v_mov_b32_e32 v31, v185
	v_mov_b32_e32 v32, v185
	v_mov_b32_e32 v33, v185
	v_mov_b32_e32 v2, 0
	v_mov_b32_e32 v3, v185
	v_mov_b32_e32 v4, v185
	v_mov_b32_e32 v5, v185
	v_mov_b32_e32 v6, v185
	v_mov_b32_e32 v7, v185
	v_mov_b32_e32 v8, v185
	v_mov_b32_e32 v9, v185
	v_mov_b32_e32 v10, v185
	v_mov_b32_e32 v11, v185
	v_mov_b32_e32 v12, v185
	v_mov_b32_e32 v13, v185
	v_mov_b32_e32 v14, v185
	v_mov_b32_e32 v15, v185
	v_mov_b32_e32 v16, v185
	v_mov_b32_e32 v17, v185
	s_waitcnt lgkmcnt(0)
	s_barrier
	v_mov_b32_e32 v200, 0
	v_mov_b32_e32 v201, 0
	v_mov_b32_e32 v202, 0
	v_mov_b32_e32 v203, 0
	v_mov_b32_e32 v204, 0
	v_mov_b32_e32 v205, 0
	v_mov_b32_e32 v206, 0
	v_mov_b32_e32 v207, 0
	v_mov_b32_e32 v208, 0
	v_mov_b32_e32 v209, 0
	v_mov_b32_e32 v210, 0
	v_mov_b32_e32 v211, 0
	v_mov_b32_e32 v212, 0
	v_mov_b32_e32 v213, 0
	v_mov_b32_e32 v214, 0
	v_mov_b32_e32 v215, 0
	v_mov_b32_e32 v242, 0
	v_mov_b32_e32 v243, 0
	v_mov_b32_e32 v244, 0
	v_mov_b32_e32 v245, 0
	v_lshl_add_u32 v186, v186, 1, 64
	v_add_u32_e32 v187, 0xac00, v186
	v_lshl_add_u32 v188, v188, 1, 64
	v_add_u32_e32 v197, 0xac00, v188
	v_lshl_add_u32 v190, v190, 1, 64
	v_add_u32_e32 v198, 0xac00, v190
	v_lshl_add_u32 v184, v184, 1, 64
	v_add_u32_e32 v199, 0xac00, v184
	v_add3_u32 v191, 64, v0, v191
	v_add_u32_e32 v221, 0xac00, v191
	v_add_u32_e32 v220, v191, v189
	v_add_u32_e32 v189, v221, v189
	s_add_u32 vcc_lo, s22, s62
	s_addc_u32 vcc_hi, s23, s63
;     ...
;       for (int i = 0; i < 4; ++i) kf[0][i] = *(const bf16x8*)(Ks + r * KST + kcol_off + 16 * i + 8 * h);
; #pragma unroll
;       for (int g = 0; g < NBAT; ++g) {
;         if (g + 1 < NBAT) {
;           const int t2n = (g + 1) / BPT, bn = (g + 1) % BPT;
; #pragma unroll
;           for (int i = 0; i < 4; ++i) kf[(g + 1) & 1][i] = *(const bf16x8*)(Ks + (32 * t2n + r) * KST + kcol_off + 16 * (4 * bn + i) + 8 * h);
;         }
;         __builtin_amdgcn_sched_barrier(0);
;         const int t2 = g / BPT, b = g % BPT;
; #pragma unroll
;         for (int i = 0; i < 4; ++i) st[t2] = MFMA32(kf[g & 1][i], qf[4 * b + i], st[t2]);
;         __builtin_amdgcn_sched_barrier(0);
;       }
;     ...
;       float ls = 0.f;
; #pragma unroll
;       for (int t2 = 0; t2 < 2; ++t2)
; #pragma unroll
;         for (int e = 0; e < 16; ++e) { float p = __builtin_amdgcn_exp2f(st[t2][e]); st[t2][e] = p; ls += p; }
;       l_run += ls;
;     } else {
;       float mx = st[0][0];
; #pragma unroll
;       for (int t2 = 0; t2 < 2; ++t2)
; #pragma unroll
;         for (int e = 0; e < 16; ++e) mx = fmaxf(mx, st[t2][e]);
;       mx = fmaxf(mx, shx(mx, 32));
;       float mnew = fmaxf(m_run, mx);
;       float alpha = __builtin_amdgcn_exp2f(m_run - mnew);
;       const bool changed = mnew > m_run;
;       m_run = mnew;
;       float ls = 0.f;
; #pragma unroll
;       for (int t2 = 0; t2 < 2; ++t2)
; #pragma unroll
;         for (int e = 0; e < 16; ++e) { float p = __builtin_amdgcn_exp2f(st[t2][e] - mnew); st[t2][e] = p; ls += p; }
;       l_run = l_run * alpha + ls;
;       if (__any(changed)) {
; #pragma unroll
;         for (int dt = 0; dt < 4; ++dt)
; #pragma unroll
;           for (int e = 0; e < 16; ++e) o[dt][e] *= alpha;
;       }
;     }
; #pragma unroll
;     for (int c = 0; c < 4; ++c) {
;       const int t2 = c >> 1, s2 = c & 1;
;       if (c + 1 < 4) {
; #pragma unroll
;         for (int dt = 0; dt < 4; ++dt) vf[(c + 1) & 1][dt] = *(const bf16x8*)(Vs + (32 * dt + r) * 72 + 16 * (c + 1) + 8 * h);
;       }
;       u32x4 pk;
;       pk.x = pack2(st[t2][8 * s2], st[t2][8 * s2 + 1]); pk.y = pack2(st[t2][8 * s2 + 2], st[t2][8 * s2 + 3]);
;       pk.z = pack2(st[t2][8 * s2 + 4], st[t2][8 * s2 + 5]); pk.w = pack2(st[t2][8 * s2 + 6], st[t2][8 * s2 + 7]);
;       bf16x8 pf = __builtin_bit_cast(bf16x8, pk);
;       __builtin_amdgcn_sched_barrier(0);
; #pragma unroll
.LBB0_590:
	ds_read_b128 v[98:101], v191
	ds_read_b128 v[102:105], v191 offset:32
	ds_read_b128 v[106:109], v191 offset:64
	ds_read_b128 v[110:113], v191 offset:96
	ds_read_b128 v[216:219], v191 offset:256
	ds_read_b128 v[224:227], v191 offset:288
	ds_read_b128 v[230:233], v191 offset:320
	ds_read_b128 v[238:241], v191 offset:352
	v_mfma_f32_32x32x16_bf16 v[50:65], v[200:203], v[242:245], v[50:65]
	ds_read_b128 v[200:203], v191 offset:128
	v_mfma_f32_32x32x16_bf16 v[34:49], v[204:207], v[242:245], v[34:49]
	ds_read_b128 v[204:207], v191 offset:160
	s_waitcnt vmcnt(0)
	v_mfma_f32_32x32x16_bf16 v[18:33], v[208:211], v[242:245], v[18:33]
	ds_read_b128 v[208:211], v191 offset:192
	ds_write_b128 v187, v[166:169]
	ds_write_b128 v197, v[162:165]
	v_mfma_f32_32x32x16_bf16 v[2:17], v[212:215], v[242:245], v[2:17]
	ds_read_b128 v[212:215], v191 offset:224
	ds_write_b128 v198, v[170:173]
	ds_write_b128 v199, v[174:177] offset:25600
	s_waitcnt lgkmcnt(15)
	v_mfma_f32_32x32x16_bf16 v[82:97], v[98:101], v[114:117], v[66:81]
	ds_write_b128 v199, v[178:181] offset:34816
	s_waitcnt lgkmcnt(15)
	v_mfma_f32_32x32x16_bf16 v[82:97], v[102:105], v[118:121], v[82:97]
	s_waitcnt lgkmcnt(14)
	v_mfma_f32_32x32x16_bf16 v[82:97], v[106:109], v[122:125], v[82:97]
	s_waitcnt lgkmcnt(13)
	v_mfma_f32_32x32x16_bf16 v[82:97], v[110:113], v[126:129], v[82:97]
	s_cmp_gt_u32 s21, 61
	s_cbranch_scc1 .Lmla_skip_gb0
	global_load_dwordx4 v[166:169], v194, vcc
	global_load_dwordx4 v[162:165], v195, vcc
	global_load_dwordx4 v[170:173], v196, vcc
	global_load_dwordx4 v[174:177], v192, s[100:101] offset:512
	global_load_dwordx4 v[178:181], v193, s[100:101] offset:512
.Lmla_skip_gb0:
	s_add_u32 vcc_lo, vcc_lo, s92
	s_addc_u32 vcc_hi, vcc_hi, s93
	s_add_u32 s100, s100, s30
	s_addc_u32 s101, s101, s31
	s_waitcnt lgkmcnt(8)
	v_mfma_f32_32x32x16_bf16 v[82:97], v[200:203], v[130:133], v[82:97]
	ds_read_b128 v[200:203], v191 offset:12800
	s_waitcnt lgkmcnt(8)
	v_mfma_f32_32x32x16_bf16 v[82:97], v[204:207], v[134:137], v[82:97]
	ds_read_b128 v[204:207], v191 offset:12832
	s_waitcnt lgkmcnt(8)
	v_mfma_f32_32x32x16_bf16 v[82:97], v[208:211], v[138:141], v[82:97]
	ds_read_b128 v[208:211], v191 offset:12864
	s_waitcnt lgkmcnt(6)
	v_mfma_f32_32x32x16_bf16 v[82:97], v[212:215], v[142:145], v[82:97]
	ds_read_b128 v[212:215], v191 offset:12896
	v_mfma_f32_32x32x16_bf16 v[82:97], v[216:219], v[146:149], v[82:97]
	ds_read_b128 v[216:219], v191 offset:12928
	v_mfma_f32_32x32x16_bf16 v[82:97], v[224:227], v[154:157], v[82:97]
	ds_read_b128 v[224:227], v191 offset:12960
	v_mfma_f32_32x32x16_bf16 v[82:97], v[230:233], v[150:153], v[82:97]
	ds_read_b128 v[230:233], v191 offset:12992
	v_mfma_f32_32x32x16_bf16 v[82:97], v[238:241], v[158:161], v[82:97]
	ds_read_b128 v[238:241], v191 offset:13024
	s_waitcnt lgkmcnt(7)
	v_mfma_f32_32x32x16_bf16 v[98:113], v[200:203], v[114:117], v[66:81]
	ds_read_b128 v[200:203], v191 offset:13056
	s_waitcnt lgkmcnt(7)
	v_mfma_f32_32x32x16_bf16 v[98:113], v[204:207], v[118:121], v[98:113]
	ds_read_b128 v[204:207], v191 offset:13088
	s_waitcnt lgkmcnt(7)
	v_mfma_f32_32x32x16_bf16 v[98:113], v[208:211], v[122:125], v[98:113]
	ds_read_b128 v[208:211], v191 offset:13120
	s_waitcnt lgkmcnt(7)
	v_mfma_f32_32x32x16_bf16 v[98:113], v[212:215], v[126:129], v[98:113]
	ds_read_b128 v[212:215], v191 offset:13152
	v_exp_f32_e32 v82, v82
	v_exp_f32_e32 v83, v83
	s_waitcnt lgkmcnt(7)
	v_mfma_f32_32x32x16_bf16 v[98:113], v[216:219], v[130:133], v[98:113]
	ds_read_b128 v[216:219], v220 offset:25600
	v_exp_f32_e32 v84, v84
	v_exp_f32_e32 v85, v85
	s_waitcnt lgkmcnt(7)
	v_mfma_f32_32x32x16_bf16 v[98:113], v[224:227], v[134:137], v[98:113]
	ds_read_b128 v[224:227], v220 offset:30208
	v_exp_f32_e32 v86, v86
	v_exp_f32_e32 v87, v87
	s_waitcnt lgkmcnt(7)
	v_mfma_f32_32x32x16_bf16 v[98:113], v[230:233], v[138:141], v[98:113]
	ds_read_b128 v[230:233], v220 offset:34816
	v_exp_f32_e32 v88, v88
	v_exp_f32_e32 v89, v89
	s_waitcnt lgkmcnt(7)
	v_mfma_f32_32x32x16_bf16 v[98:113], v[238:241], v[142:145], v[98:113]
	ds_read_b128 v[238:241], v220 offset:39424
	v_exp_f32_e32 v90, v90
	v_exp_f32_e32 v91, v91
	v_cvt_pk_bf16_f32 v242, v82, v83
	s_waitcnt lgkmcnt(7)
	v_mfma_f32_32x32x16_bf16 v[98:113], v[200:203], v[146:149], v[98:113]
	ds_read_b128 v[200:203], v220 offset:25632
	v_exp_f32_e32 v92, v92
	v_exp_f32_e32 v93, v93
	v_cvt_pk_bf16_f32 v243, v84, v85
	s_waitcnt lgkmcnt(7)
	v_mfma_f32_32x32x16_bf16 v[98:113], v[204:207], v[154:157], v[98:113]
	ds_read_b128 v[204:207], v220 offset:30240
	v_exp_f32_e32 v94, v94
	v_exp_f32_e32 v95, v95
	v_cvt_pk_bf16_f32 v244, v86, v87
	s_waitcnt lgkmcnt(7)
	v_mfma_f32_32x32x16_bf16 v[98:113], v[208:211], v[150:153], v[98:113]
	ds_read_b128 v[208:211], v220 offset:34848
	v_exp_f32_e32 v96, v96
	v_exp_f32_e32 v97, v97
	v_cvt_pk_bf16_f32 v245, v88, v89
	s_waitcnt lgkmcnt(7)
	v_mfma_f32_32x32x16_bf16 v[98:113], v[212:215], v[158:161], v[98:113]
	ds_read_b128 v[212:215], v220 offset:39456
	v_add_f32_e32 v246, v90, v91
	v_add_f32_e32 v246, v92, v246
	v_add_f32_e32 v246, v93, v246
	v_add_f32_e32 v246, v94, v246
	s_waitcnt lgkmcnt(7)
	v_mfma_f32_32x32x16_bf16 v[50:65], v[216:219], v[242:245], v[50:65]
	ds_read_b128 v[216:219], v220 offset:25664
	v_add_f32_e32 v246, v95, v246
	v_add_f32_e32 v246, v96, v246
	v_add_f32_e32 v246, v97, v246
	v_cvt_pk_bf16_f32 v90, v90, v91
	v_cvt_pk_bf16_f32 v91, v92, v93
	s_waitcnt lgkmcnt(7)
	v_mfma_f32_32x32x16_bf16 v[34:49], v[224:227], v[242:245], v[34:49]
	ds_read_b128 v[224:227], v220 offset:30272
	v_cvt_pk_bf16_f32 v92, v94, v95
	v_cvt_pk_bf16_f32 v93, v96, v97
	v_exp_f32_e32 v98, v98
	v_exp_f32_e32 v99, v99
	s_waitcnt lgkmcnt(7)
; #define MFMA32(a, b, c) __builtin_amdgcn_mfma_f32_32x32x16_bf16((a), (b), (c), 0, 0, 0)
; DI u32 pack2(float a, float b) { f2_t v = {a, b}; bf2_t r = __builtin_convertvector(v, bf2_t); return __builtin_bit_cast(u32, r); }
; DI float shx(float v, int k) { return __int_as_float(__builtin_amdgcn_ds_bpermute((lane_id_l() ^ k) << 2, __float_as_int(v))); }
;     ...
;       float ls = 0.f;
; #pragma unroll
;       for (int t2 = 0; t2 < 2; ++t2)
; #pragma unroll
;         for (int e = 0; e < 16; ++e) { float p = __builtin_amdgcn_exp2f(st[t2][e]); st[t2][e] = p; ls += p; }
;       l_run += ls;
;     } else {
;       float mx = st[0][0];
; #pragma unroll
;       for (int t2 = 0; t2 < 2; ++t2)
; #pragma unroll
;         for (int e = 0; e < 16; ++e) mx = fmaxf(mx, st[t2][e]);
;       mx = fmaxf(mx, shx(mx, 32));
;       float mnew = fmaxf(m_run, mx);
;       float alpha = __builtin_amdgcn_exp2f(m_run - mnew);
;       const bool changed = mnew > m_run;
;       m_run = mnew;
;       float ls = 0.f;
; #pragma unroll
;       for (int t2 = 0; t2 < 2; ++t2)
; #pragma unroll
;         for (int e = 0; e < 16; ++e) { float p = __builtin_amdgcn_exp2f(st[t2][e] - mnew); st[t2][e] = p; ls += p; }
;       l_run = l_run * alpha + ls;
;       if (__any(changed)) {
; #pragma unroll
;         for (int dt = 0; dt < 4; ++dt)
; #pragma unroll
;           for (int e = 0; e < 16; ++e) o[dt][e] *= alpha;
;       }
;     }
; #pragma unroll
;     for (int c = 0; c < 4; ++c) {
;       const int t2 = c >> 1, s2 = c & 1;
;       if (c + 1 < 4) {
; #pragma unroll
;         for (int dt = 0; dt < 4; ++dt) vf[(c + 1) & 1][dt] = *(const bf16x8*)(Vs + (32 * dt + r) * 72 + 16 * (c + 1) + 8 * h);
;       }
;       u32x4 pk;
;       pk.x = pack2(st[t2][8 * s2], st[t2][8 * s2 + 1]); pk.y = pack2(st[t2][8 * s2 + 2], st[t2][8 * s2 + 3]);
;       pk.z = pack2(st[t2][8 * s2 + 4], st[t2][8 * s2 + 5]); pk.w = pack2(st[t2][8 * s2 + 6], st[t2][8 * s2 + 7]);
;       bf16x8 pf = __builtin_bit_cast(bf16x8, pk);
;       __builtin_amdgcn_sched_barrier(0);
; #pragma unroll
;       for (int dt = 0; dt < 4; ++dt) o[dt] = MFMA32(vf[c & 1][dt], pf, o[dt]);
;       __builtin_amdgcn_sched_barrier(0);
;     }
;     if (kt + 1 < nkt) lstore((kt + 1) & 1);
;     if (kt + 2 < nkt) gload((kt0 + kt + 2) * 64);
;     __syncthreads();
	v_mfma_f32_32x32x16_bf16 v[18:33], v[230:233], v[242:245], v[18:33]
	ds_read_b128 v[230:233], v220 offset:34880
	v_exp_f32_e32 v100, v100
	v_exp_f32_e32 v101, v101
	v_exp_f32_e32 v102, v102
	s_waitcnt lgkmcnt(7)
	v_mfma_f32_32x32x16_bf16 v[2:17], v[238:241], v[242:245], v[2:17]
	ds_read_b128 v[238:241], v220 offset:39488
	v_exp_f32_e32 v103, v103
	v_exp_f32_e32 v104, v104
	v_exp_f32_e32 v105, v105
	s_waitcnt lgkmcnt(7)
	v_mfma_f32_32x32x16_bf16 v[50:65], v[200:203], v[90:93], v[50:65]
	ds_read_b128 v[200:203], v220 offset:25696
	v_cvt_pk_bf16_f32 v94, v98, v99
	v_cvt_pk_bf16_f32 v95, v100, v101
	v_cvt_pk_bf16_f32 v96, v102, v103
	v_cvt_pk_bf16_f32 v97, v104, v105
	v_exp_f32_e32 v106, v106
	s_waitcnt lgkmcnt(7)
	v_mfma_f32_32x32x16_bf16 v[34:49], v[204:207], v[90:93], v[34:49]
	ds_read_b128 v[204:207], v220 offset:30304
	v_exp_f32_e32 v107, v107
	v_exp_f32_e32 v108, v108
	v_exp_f32_e32 v109, v109
	v_add_f32_e32 v246, v82, v246
	s_waitcnt lgkmcnt(7)
	v_mfma_f32_32x32x16_bf16 v[18:33], v[208:211], v[90:93], v[18:33]
	ds_read_b128 v[208:211], v220 offset:34912
	v_exp_f32_e32 v110, v110
	v_exp_f32_e32 v111, v111
	v_exp_f32_e32 v112, v112
	v_add_f32_e32 v246, v83, v246
	s_waitcnt lgkmcnt(7)
	v_mfma_f32_32x32x16_bf16 v[2:17], v[212:215], v[90:93], v[2:17]
	ds_read_b128 v[212:215], v220 offset:39520
	v_exp_f32_e32 v113, v113
	v_add_f32_e32 v247, v106, v107
	v_add_f32_e32 v247, v108, v247
	v_add_f32_e32 v246, v84, v246
	s_waitcnt lgkmcnt(7)
	v_mfma_f32_32x32x16_bf16 v[50:65], v[216:219], v[94:97], v[50:65]
	v_add_f32_e32 v247, v109, v247
	v_add_f32_e32 v247, v110, v247
	v_add_f32_e32 v247, v111, v247
	v_add_f32_e32 v247, v112, v247
	v_add_f32_e32 v247, v113, v247
	v_add_f32_e32 v246, v85, v246
	s_waitcnt lgkmcnt(6)
	v_mfma_f32_32x32x16_bf16 v[34:49], v[224:227], v[94:97], v[34:49]
	v_cvt_pk_bf16_f32 v242, v106, v107
	v_cvt_pk_bf16_f32 v243, v108, v109
	v_cvt_pk_bf16_f32 v244, v110, v111
	v_cvt_pk_bf16_f32 v245, v112, v113
	v_add_f32_e32 v247, v98, v247
	v_add_f32_e32 v246, v86, v246
	v_add_f32_e32 v247, v99, v247
	s_waitcnt lgkmcnt(5)
	v_mfma_f32_32x32x16_bf16 v[18:33], v[230:233], v[94:97], v[18:33]
	v_add_f32_e32 v247, v100, v247
	v_add_f32_e32 v246, v87, v246
	v_add_f32_e32 v247, v101, v247
	v_add_f32_e32 v246, v88, v246
	v_add_f32_e32 v247, v102, v247
	v_add_f32_e32 v246, v89, v246
	v_add_f32_e32 v247, v103, v247
	s_waitcnt lgkmcnt(4)
	v_mfma_f32_32x32x16_bf16 v[2:17], v[238:241], v[94:97], v[2:17]
	v_add_f32_e32 v247, v104, v247
	v_add_f32_e32 v247, v105, v247
	v_add_f32_e32 v246, v247, v246
	v_add_f32_e32 v185, v185, v246
	s_waitcnt lgkmcnt(0)
	s_barrier
	ds_read_b128 v[98:101], v221
	ds_read_b128 v[102:105], v221 offset:32
	ds_read_b128 v[106:109], v221 offset:64
	ds_read_b128 v[110:113], v221 offset:96
	ds_read_b128 v[216:219], v221 offset:256
	ds_read_b128 v[224:227], v221 offset:288
	ds_read_b128 v[230:233], v221 offset:320
	ds_read_b128 v[238:241], v221 offset:352
	v_mfma_f32_32x32x16_bf16 v[50:65], v[200:203], v[242:245], v[50:65]
	ds_read_b128 v[200:203], v221 offset:128
	v_mfma_f32_32x32x16_bf16 v[34:49], v[204:207], v[242:245], v[34:49]
	ds_read_b128 v[204:207], v221 offset:160
	s_waitcnt vmcnt(0)
	v_mfma_f32_32x32x16_bf16 v[18:33], v[208:211], v[242:245], v[18:33]
	ds_read_b128 v[208:211], v221 offset:192
	ds_write_b128 v186, v[166:169]
	ds_write_b128 v188, v[162:165]
	v_mfma_f32_32x32x16_bf16 v[2:17], v[212:215], v[242:245], v[2:17]
	ds_read_b128 v[212:215], v221 offset:224
	ds_write_b128 v190, v[170:173]
	ds_write_b128 v184, v[174:177] offset:25600
	s_waitcnt lgkmcnt(15)
	v_mfma_f32_32x32x16_bf16 v[82:97], v[98:101], v[114:117], v[66:81]
	ds_write_b128 v184, v[178:181] offset:34816
	s_waitcnt lgkmcnt(15)
	v_mfma_f32_32x32x16_bf16 v[82:97], v[102:105], v[118:121], v[82:97]
	s_waitcnt lgkmcnt(14)
	v_mfma_f32_32x32x16_bf16 v[82:97], v[106:109], v[122:125], v[82:97]
	s_waitcnt lgkmcnt(13)
	v_mfma_f32_32x32x16_bf16 v[82:97], v[110:113], v[126:129], v[82:97]
	s_cmp_gt_u32 s21, 61
	s_cbranch_scc1 .Lmla_skip_gb1
	global_load_dwordx4 v[166:169], v194, vcc
	global_load_dwordx4 v[162:165], v195, vcc
	global_load_dwordx4 v[170:173], v196, vcc
	global_load_dwordx4 v[174:177], v192, s[100:101] offset:512
	global_load_dwordx4 v[178:181], v193, s[100:101] offset:512
;     ...
;       for (int i = 0; i < 4; ++i) kf[0][i] = *(const bf16x8*)(Ks + r * KST + kcol_off + 16 * i + 8 * h);
; #pragma unroll
;       for (int g = 0; g < NBAT; ++g) {
;         if (g + 1 < NBAT) {
;           const int t2n = (g + 1) / BPT, bn = (g + 1) % BPT;
; #pragma unroll
;           for (int i = 0; i < 4; ++i) kf[(g + 1) & 1][i] = *(const bf16x8*)(Ks + (32 * t2n + r) * KST + kcol_off + 16 * (4 * bn + i) + 8 * h);
;         }
;         __builtin_amdgcn_sched_barrier(0);
;         const int t2 = g / BPT, b = g % BPT;
; #pragma unroll
;         for (int i = 0; i < 4; ++i) st[t2] = MFMA32(kf[g & 1][i], qf[4 * b + i], st[t2]);
;         __builtin_amdgcn_sched_barrier(0);
;       }
;     ...
;       float ls = 0.f;
; #pragma unroll
;       for (int t2 = 0; t2 < 2; ++t2)
; #pragma unroll
;         for (int e = 0; e < 16; ++e) { float p = __builtin_amdgcn_exp2f(st[t2][e]); st[t2][e] = p; ls += p; }
;       l_run += ls;
;     } else {
;       float mx = st[0][0];
; #pragma unroll
;       for (int t2 = 0; t2 < 2; ++t2)
; #pragma unroll
;         for (int e = 0; e < 16; ++e) mx = fmaxf(mx, st[t2][e]);
;       mx = fmaxf(mx, shx(mx, 32));
;       float mnew = fmaxf(m_run, mx);
;       float alpha = __builtin_amdgcn_exp2f(m_run - mnew);
;       const bool changed = mnew > m_run;
;       m_run = mnew;
;       float ls = 0.f;
; #pragma unroll
;       for (int t2 = 0; t2 < 2; ++t2)
; #pragma unroll
;         for (int e = 0; e < 16; ++e) { float p = __builtin_amdgcn_exp2f(st[t2][e] - mnew); st[t2][e] = p; ls += p; }
;       l_run = l_run * alpha + ls;
;       if (__any(changed)) {
; #pragma unroll
;         for (int dt = 0; dt < 4; ++dt)
; #pragma unroll
;           for (int e = 0; e < 16; ++e) o[dt][e] *= alpha;
;       }
;     }
; #pragma unroll
;     for (int c = 0; c < 4; ++c) {
;       const int t2 = c >> 1, s2 = c & 1;
;       if (c + 1 < 4) {
; #pragma unroll
;         for (int dt = 0; dt < 4; ++dt) vf[(c + 1) & 1][dt] = *(const bf16x8*)(Vs + (32 * dt + r) * 72 + 16 * (c + 1) + 8 * h);
;       }
;       u32x4 pk;
;       pk.x = pack2(st[t2][8 * s2], st[t2][8 * s2 + 1]); pk.y = pack2(st[t2][8 * s2 + 2], st[t2][8 * s2 + 3]);
;       pk.z = pack2(st[t2][8 * s2 + 4], st[t2][8 * s2 + 5]); pk.w = pack2(st[t2][8 * s2 + 6], st[t2][8 * s2 + 7]);
;       bf16x8 pf = __builtin_bit_cast(bf16x8, pk);
;       __builtin_amdgcn_sched_barrier(0);
; #pragma unroll
.Lmla_skip_gb1:
	s_add_u32 vcc_lo, vcc_lo, s92
	s_addc_u32 vcc_hi, vcc_hi, s93
	s_add_u32 s100, s100, s30
	s_addc_u32 s101, s101, s31
	s_waitcnt lgkmcnt(8)
	v_mfma_f32_32x32x16_bf16 v[82:97], v[200:203], v[130:133], v[82:97]
	ds_read_b128 v[200:203], v221 offset:12800
	s_waitcnt lgkmcnt(8)
	v_mfma_f32_32x32x16_bf16 v[82:97], v[204:207], v[134:137], v[82:97]
	ds_read_b128 v[204:207], v221 offset:12832
	s_waitcnt lgkmcnt(8)
	v_mfma_f32_32x32x16_bf16 v[82:97], v[208:211], v[138:141], v[82:97]
	ds_read_b128 v[208:211], v221 offset:12864
	s_waitcnt lgkmcnt(6)
	v_mfma_f32_32x32x16_bf16 v[82:97], v[212:215], v[142:145], v[82:97]
	ds_read_b128 v[212:215], v221 offset:12896
	v_mfma_f32_32x32x16_bf16 v[82:97], v[216:219], v[146:149], v[82:97]
	ds_read_b128 v[216:219], v221 offset:12928
	v_mfma_f32_32x32x16_bf16 v[82:97], v[224:227], v[154:157], v[82:97]
	ds_read_b128 v[224:227], v221 offset:12960
	v_mfma_f32_32x32x16_bf16 v[82:97], v[230:233], v[150:153], v[82:97]
	ds_read_b128 v[230:233], v221 offset:12992
	v_mfma_f32_32x32x16_bf16 v[82:97], v[238:241], v[158:161], v[82:97]
	ds_read_b128 v[238:241], v221 offset:13024
	s_waitcnt lgkmcnt(7)
	v_mfma_f32_32x32x16_bf16 v[98:113], v[200:203], v[114:117], v[66:81]
	ds_read_b128 v[200:203], v221 offset:13056
	s_waitcnt lgkmcnt(7)
	v_mfma_f32_32x32x16_bf16 v[98:113], v[204:207], v[118:121], v[98:113]
	ds_read_b128 v[204:207], v221 offset:13088
	s_waitcnt lgkmcnt(7)
	v_mfma_f32_32x32x16_bf16 v[98:113], v[208:211], v[122:125], v[98:113]
	ds_read_b128 v[208:211], v221 offset:13120
	s_waitcnt lgkmcnt(7)
	v_mfma_f32_32x32x16_bf16 v[98:113], v[212:215], v[126:129], v[98:113]
	ds_read_b128 v[212:215], v221 offset:13152
	v_exp_f32_e32 v82, v82
	v_exp_f32_e32 v83, v83
	s_waitcnt lgkmcnt(7)
	v_mfma_f32_32x32x16_bf16 v[98:113], v[216:219], v[130:133], v[98:113]
	ds_read_b128 v[216:219], v189 offset:25600
	v_exp_f32_e32 v84, v84
	v_exp_f32_e32 v85, v85
	s_waitcnt lgkmcnt(7)
	v_mfma_f32_32x32x16_bf16 v[98:113], v[224:227], v[134:137], v[98:113]
	ds_read_b128 v[224:227], v189 offset:30208
	v_exp_f32_e32 v86, v86
	v_exp_f32_e32 v87, v87
	s_waitcnt lgkmcnt(7)
	v_mfma_f32_32x32x16_bf16 v[98:113], v[230:233], v[138:141], v[98:113]
	ds_read_b128 v[230:233], v189 offset:34816
	v_exp_f32_e32 v88, v88
	v_exp_f32_e32 v89, v89
	s_waitcnt lgkmcnt(7)
	v_mfma_f32_32x32x16_bf16 v[98:113], v[238:241], v[142:145], v[98:113]
	ds_read_b128 v[238:241], v189 offset:39424
	v_exp_f32_e32 v90, v90
	v_exp_f32_e32 v91, v91
	v_cvt_pk_bf16_f32 v242, v82, v83
	s_waitcnt lgkmcnt(7)
	v_mfma_f32_32x32x16_bf16 v[98:113], v[200:203], v[146:149], v[98:113]
	ds_read_b128 v[200:203], v189 offset:25632
	v_exp_f32_e32 v92, v92
	v_exp_f32_e32 v93, v93
	v_cvt_pk_bf16_f32 v243, v84, v85
	s_waitcnt lgkmcnt(7)
	v_mfma_f32_32x32x16_bf16 v[98:113], v[204:207], v[154:157], v[98:113]
	ds_read_b128 v[204:207], v189 offset:30240
	v_exp_f32_e32 v94, v94
	v_exp_f32_e32 v95, v95
	v_cvt_pk_bf16_f32 v244, v86, v87
	s_waitcnt lgkmcnt(7)
	v_mfma_f32_32x32x16_bf16 v[98:113], v[208:211], v[150:153], v[98:113]
	ds_read_b128 v[208:211], v189 offset:34848
	v_exp_f32_e32 v96, v96
	v_exp_f32_e32 v97, v97
	v_cvt_pk_bf16_f32 v245, v88, v89
	s_waitcnt lgkmcnt(7)
	v_mfma_f32_32x32x16_bf16 v[98:113], v[212:215], v[158:161], v[98:113]
	ds_read_b128 v[212:215], v189 offset:39456
	v_add_f32_e32 v246, v90, v91
	v_add_f32_e32 v246, v92, v246
	v_add_f32_e32 v246, v93, v246
	v_add_f32_e32 v246, v94, v246
	s_waitcnt lgkmcnt(7)
	v_mfma_f32_32x32x16_bf16 v[50:65], v[216:219], v[242:245], v[50:65]
	ds_read_b128 v[216:219], v189 offset:25664
	v_add_f32_e32 v246, v95, v246
	v_add_f32_e32 v246, v96, v246
	v_add_f32_e32 v246, v97, v246
	v_cvt_pk_bf16_f32 v90, v90, v91
	v_cvt_pk_bf16_f32 v91, v92, v93
	s_waitcnt lgkmcnt(7)
	v_mfma_f32_32x32x16_bf16 v[34:49], v[224:227], v[242:245], v[34:49]
	ds_read_b128 v[224:227], v189 offset:30272
	v_cvt_pk_bf16_f32 v92, v94, v95
	v_cvt_pk_bf16_f32 v93, v96, v97
	v_exp_f32_e32 v98, v98
	v_exp_f32_e32 v99, v99
	s_waitcnt lgkmcnt(7)
	v_mfma_f32_32x32x16_bf16 v[18:33], v[230:233], v[242:245], v[18:33]
	ds_read_b128 v[230:233], v189 offset:34880
	v_exp_f32_e32 v100, v100
	v_exp_f32_e32 v101, v101
	v_exp_f32_e32 v102, v102
	s_waitcnt lgkmcnt(7)
	v_mfma_f32_32x32x16_bf16 v[2:17], v[238:241], v[242:245], v[2:17]
	ds_read_b128 v[238:241], v189 offset:39488
	v_exp_f32_e32 v103, v103
	v_exp_f32_e32 v104, v104
	v_exp_f32_e32 v105, v105
	s_waitcnt lgkmcnt(7)
	v_mfma_f32_32x32x16_bf16 v[50:65], v[200:203], v[90:93], v[50:65]
	ds_read_b128 v[200:203], v189 offset:25696
	v_cvt_pk_bf16_f32 v94, v98, v99
	v_cvt_pk_bf16_f32 v95, v100, v101
	v_cvt_pk_bf16_f32 v96, v102, v103
	v_cvt_pk_bf16_f32 v97, v104, v105
	v_exp_f32_e32 v106, v106
	s_waitcnt lgkmcnt(7)
	v_mfma_f32_32x32x16_bf16 v[34:49], v[204:207], v[90:93], v[34:49]
	ds_read_b128 v[204:207], v189 offset:30304
	v_exp_f32_e32 v107, v107
	v_exp_f32_e32 v108, v108
	v_exp_f32_e32 v109, v109
	v_add_f32_e32 v246, v82, v246
	s_waitcnt lgkmcnt(7)
	v_mfma_f32_32x32x16_bf16 v[18:33], v[208:211], v[90:93], v[18:33]
	ds_read_b128 v[208:211], v189 offset:34912
	v_exp_f32_e32 v110, v110
	v_exp_f32_e32 v111, v111
	v_exp_f32_e32 v112, v112
	v_add_f32_e32 v246, v83, v246
	s_waitcnt lgkmcnt(7)
	v_mfma_f32_32x32x16_bf16 v[2:17], v[212:215], v[90:93], v[2:17]
	ds_read_b128 v[212:215], v189 offset:39520
	v_exp_f32_e32 v113, v113
	v_add_f32_e32 v247, v106, v107
	v_add_f32_e32 v247, v108, v247
	v_add_f32_e32 v246, v84, v246
	s_waitcnt lgkmcnt(7)
	v_mfma_f32_32x32x16_bf16 v[50:65], v[216:219], v[94:97], v[50:65]
	v_add_f32_e32 v247, v109, v247
	v_add_f32_e32 v247, v110, v247
	v_add_f32_e32 v247, v111, v247
	v_add_f32_e32 v247, v112, v247
	v_add_f32_e32 v247, v113, v247
	v_add_f32_e32 v246, v85, v246
	s_waitcnt lgkmcnt(6)
	v_mfma_f32_32x32x16_bf16 v[34:49], v[224:227], v[94:97], v[34:49]
	v_cvt_pk_bf16_f32 v242, v106, v107
	v_cvt_pk_bf16_f32 v243, v108, v109
	v_cvt_pk_bf16_f32 v244, v110, v111
	v_cvt_pk_bf16_f32 v245, v112, v113
	v_add_f32_e32 v247, v98, v247
	v_add_f32_e32 v246, v86, v246
	v_add_f32_e32 v247, v99, v247
	s_waitcnt lgkmcnt(5)
	v_mfma_f32_32x32x16_bf16 v[18:33], v[230:233], v[94:97], v[18:33]
	v_add_f32_e32 v247, v100, v247
	v_add_f32_e32 v246, v87, v246
	v_add_f32_e32 v247, v101, v247
	v_add_f32_e32 v246, v88, v246
	v_add_f32_e32 v247, v102, v247
	v_add_f32_e32 v246, v89, v246
	v_add_f32_e32 v247, v103, v247
	s_waitcnt lgkmcnt(4)
	v_mfma_f32_32x32x16_bf16 v[2:17], v[238:241], v[94:97], v[2:17]
	v_add_f32_e32 v247, v104, v247
	v_add_f32_e32 v247, v105, v247
	v_add_f32_e32 v246, v247, v246
	v_add_f32_e32 v185, v185, v246
	s_add_i32 s21, s21, 2
	s_cmp_lg_u32 s21, 64
	s_waitcnt lgkmcnt(0)
	s_barrier
	s_cbranch_scc1 .LBB0_590
